# v58 + peeled first K-iteration per GEMM unit (srcC=0 for each accumulator's first MFMA; the 128 v_mov zeroing per unit removed)
# speedup vs baseline: 1.0006x; 1.0006x over previous
; #define PG8_STAGE(bufoff, gbase, voff) do { _Pragma("unroll") for (int _i = 0; _i < 2; ++_i) \
;         __builtin_amdgcn_global_load_lds((const unsigned*)((const char*)(gbase) + (voff)[_i]), (PG8_LAS unsigned*)(lds + (bufoff) + ldsw + _i * 8192), 16, 0, 0); } while (0)
; #define PG8_LDA(dst, b, h) do { _Pragma("unroll") for (int m = 0; m < 4; ++m) _Pragma("unroll") for (int k = 0; k < 2; ++k) dst[m][k] = *(const PG8_LAS bf16x8*)(lds + PG8_SA(b, h) + aoff + m * 2048 + k * 1024); } while (0)
; #define PG8_LDB(dst, b, h) do { _Pragma("unroll") for (int n = 0; n < 2; ++n) _Pragma("unroll") for (int k = 0; k < 2; ++k) dst[n][k] = *(const PG8_LAS bf16x8*)(lds + PG8_SB(b, h) + boff + n * 2048 + k * 1024); } while (0)
; #define PG8_MMA(ai, bj, At, Bt) do { __builtin_amdgcn_s_setprio(1); _Pragma("unroll") for (int m = 0; m < 4; ++m) _Pragma("unroll") for (int n = 0; n < 2; ++n) _Pragma("unroll") for (int k = 0; k < 2; ++k) \
;         acc[ai][bj][m][n] = __builtin_amdgcn_mfma_f32_16x16x32_bf16(Bt[n][k], At[m][k], acc[ai][bj][m][n], 0, 0, 0); __builtin_amdgcn_s_setprio(0); } while (0)
; #define PG8_WAIT_V(n) asm volatile("s_waitcnt vmcnt(" #n ")" ::: "memory")
; #define PG8_WAIT_L(n) asm volatile("s_waitcnt lgkmcnt(" #n ")" ::: "memory")
; #define PG8_BAR __builtin_amdgcn_s_barrier()
; #define PG8_SCHED __builtin_amdgcn_sched_barrier(0)
; template <class Epi, class Sched, bool ALIGN_EPI = false, bool SP2 = false>
; __device__ __forceinline__ void gemm_phase(PG8_LAS unsigned char* lds, const Gemm g, const Sched& S, const Epi& E) {
;     ...
;             PG8_LDB(B0, 0, 0); PG8_LDB(B1, 0, 1); PG8_SCHED; PG8_LDA(At, 0, 0); PG8_STAGE(PG8_SA(1, 1), a1 + hstep, voffA);
;             PG8_WAIT_V(8); PG8_WAIT_L(0); PG8_BAR; PG8_MMA(0, 0, At, B0); PG8_MMA(0, 1, At, B1); PG8_BAR; PG8_SCHED;
;             PG8_LDA(At, 0, 1); PG8_STAGE(PG8_SB(0, 0), b2, voffB); PG8_STAGE(PG8_SB(0, 1), b2 + hstep, voffB); PG8_STAGE(PG8_SA(0, 0), a2, voffA);
;             PG8_WAIT_V(8); PG8_WAIT_L(0); PG8_BAR; PG8_MMA(1, 0, At, B0); PG8_MMA(1, 1, At, B1); PG8_BAR; PG8_SCHED;
;     ...
;         for (int a = 0; a < 2; ++a)
; #pragma unroll
;             for (int b = 0; b < 2; ++b)
; #pragma unroll
;                 for (int m = 0; m < 4; ++m)
; #pragma unroll
;                     for (int n = 0; n < 2; ++n) acc[a][b][m][n] = (f32x4){0.f, 0.f, 0.f, 0.f};
.LBB0_348:
	s_add_u32 s88, s88, 0x100080
	s_addc_u32 s89, s89, 0
	s_add_u32 s9, s90, 0x100
	s_addc_u32 s21, s91, 0
	s_mov_b32 s23, -2
	s_cmp_lt_u32 s27, 0x1000
	s_cbranch_scc0 .Lip_h1first
	ds_read_b128 v[150:153], v169
	ds_read_b128 v[154:157], v169 offset:1024
	ds_read_b128 v[158:161], v169 offset:2048
	ds_read_b128 v[162:165], v169 offset:3072
	ds_read_b128 v[174:177], v170
	ds_read_b128 v[178:181], v170 offset:1024
	ds_read_b128 v[182:185], v170 offset:2048
	ds_read_b128 v[186:189], v170 offset:3072
	s_add_u32 s0, s88, 0xfff00080
	s_addc_u32 s1, s89, -1
	s_cmp_eq_u32 s23, 60
	s_cselect_b32 s93, s51, s1
	s_cselect_b32 s92, s50, s0
	s_cselect_b32 s91, s53, s21
	s_cselect_b32 s90, s52, s9
	ds_read_b128 v[190:193], v171
	ds_read_b128 v[196:199], v171 offset:1024
	ds_read_b128 v[200:203], v171 offset:2048
	ds_read_b128 v[204:207], v171 offset:3072
	ds_read_b128 v[208:211], v171 offset:4096
	ds_read_b128 v[212:215], v171 offset:5120
	ds_read_b128 v[220:223], v171 offset:6144
	ds_read_b128 v[224:227], v171 offset:7168
	s_add_u32 s0, s88, 0xfff00000
	s_addc_u32 s1, s89, -1
	s_add_i32 m0, s27, 0x8000
	s_nop 0
	global_load_lds_dwordx4 v134, s[0:1]
	s_add_i32 m0, s27, 0xa000
	s_nop 0
	global_load_lds_dwordx4 v138, s[0:1]
	s_add_i32 m0, s27, 0xc000
	s_nop 0
	global_load_lds_dwordx4 v134, s[88:89]
	s_add_i32 m0, s27, 0xe000
	s_nop 0
	global_load_lds_dwordx4 v138, s[88:89]
	s_waitcnt lgkmcnt(0)
	s_setprio 1
	v_mfma_f32_16x16x32_bf16 v[38:41], v[150:153], v[190:193], 0
	v_mfma_f32_16x16x32_bf16 v[38:41], v[154:157], v[196:199], v[38:41]
	v_mfma_f32_16x16x32_bf16 v[30:33], v[158:161], v[190:193], 0
	v_mfma_f32_16x16x32_bf16 v[30:33], v[162:165], v[196:199], v[30:33]
	v_mfma_f32_16x16x32_bf16 v[50:53], v[174:177], v[190:193], 0
	v_mfma_f32_16x16x32_bf16 v[50:53], v[178:181], v[196:199], v[50:53]
	v_mfma_f32_16x16x32_bf16 v[46:49], v[182:185], v[190:193], 0
	v_mfma_f32_16x16x32_bf16 v[46:49], v[186:189], v[196:199], v[46:49]
	v_mfma_f32_16x16x32_bf16 v[118:121], v[182:185], v[200:203], 0
	v_mfma_f32_16x16x32_bf16 v[118:121], v[186:189], v[204:207], v[118:121]
	v_mfma_f32_16x16x32_bf16 v[122:125], v[174:177], v[200:203], 0
	v_mfma_f32_16x16x32_bf16 v[122:125], v[178:181], v[204:207], v[122:125]
	v_mfma_f32_16x16x32_bf16 v[126:129], v[158:161], v[200:203], 0
	v_mfma_f32_16x16x32_bf16 v[126:129], v[162:165], v[204:207], v[126:129]
	v_mfma_f32_16x16x32_bf16 v[130:133], v[150:153], v[200:203], 0
	v_mfma_f32_16x16x32_bf16 v[130:133], v[154:157], v[204:207], v[130:133]
	v_mfma_f32_16x16x32_bf16 v[114:117], v[150:153], v[208:211], 0
	v_mfma_f32_16x16x32_bf16 v[114:117], v[154:157], v[212:215], v[114:117]
	v_mfma_f32_16x16x32_bf16 v[110:113], v[158:161], v[208:211], 0
	v_mfma_f32_16x16x32_bf16 v[110:113], v[162:165], v[212:215], v[110:113]
	v_mfma_f32_16x16x32_bf16 v[106:109], v[174:177], v[208:211], 0
	v_mfma_f32_16x16x32_bf16 v[106:109], v[178:181], v[212:215], v[106:109]
	v_mfma_f32_16x16x32_bf16 v[102:105], v[182:185], v[208:211], 0
	v_mfma_f32_16x16x32_bf16 v[102:105], v[186:189], v[212:215], v[102:105]
	v_mfma_f32_16x16x32_bf16 v[86:89], v[182:185], v[220:223], 0
	v_mfma_f32_16x16x32_bf16 v[86:89], v[186:189], v[224:227], v[86:89]
	v_mfma_f32_16x16x32_bf16 v[90:93], v[174:177], v[220:223], 0
	v_mfma_f32_16x16x32_bf16 v[90:93], v[178:181], v[224:227], v[90:93]
	v_mfma_f32_16x16x32_bf16 v[94:97], v[158:161], v[220:223], 0
	v_mfma_f32_16x16x32_bf16 v[94:97], v[162:165], v[224:227], v[94:97]
	v_mfma_f32_16x16x32_bf16 v[98:101], v[150:153], v[220:223], 0
	v_mfma_f32_16x16x32_bf16 v[98:101], v[154:157], v[224:227], v[98:101]
	s_setprio 0
	s_waitcnt vmcnt(8)
	s_barrier
	ds_read_b128 v[190:193], v171 offset:16384
	ds_read_b128 v[196:199], v171 offset:17408
	ds_read_b128 v[200:203], v171 offset:18432
	ds_read_b128 v[204:207], v171 offset:19456
	ds_read_b128 v[208:211], v171 offset:20480
	ds_read_b128 v[212:215], v171 offset:21504
	ds_read_b128 v[220:223], v171 offset:22528
	ds_read_b128 v[224:227], v171 offset:23552
	s_add_u32 vcc_lo, s90, 0x100000
	s_addc_u32 vcc_hi, s91, 0
	s_add_i32 m0, s27, 0x10000
	s_nop 0
	global_load_lds_dwordx4 v136, s[90:91]
	s_add_i32 m0, s27, 0x12000
	s_nop 0
	global_load_lds_dwordx4 v140, s[90:91]
	s_add_i32 m0, s27, 0x14000
	s_nop 0
	global_load_lds_dwordx4 v136, vcc
	s_add_i32 m0, s27, 0x16000
	s_nop 0
	global_load_lds_dwordx4 v140, vcc
	s_waitcnt lgkmcnt(0)
	s_setprio 1
	v_mfma_f32_16x16x32_bf16 v[82:85], v[150:153], v[190:193], 0
	v_mfma_f32_16x16x32_bf16 v[82:85], v[154:157], v[196:199], v[82:85]
	v_mfma_f32_16x16x32_bf16 v[78:81], v[158:161], v[190:193], 0
	v_mfma_f32_16x16x32_bf16 v[78:81], v[162:165], v[196:199], v[78:81]
	v_mfma_f32_16x16x32_bf16 v[74:77], v[174:177], v[190:193], 0
	v_mfma_f32_16x16x32_bf16 v[74:77], v[178:181], v[196:199], v[74:77]
	v_mfma_f32_16x16x32_bf16 v[70:73], v[182:185], v[190:193], 0
	v_mfma_f32_16x16x32_bf16 v[70:73], v[186:189], v[196:199], v[70:73]
	v_mfma_f32_16x16x32_bf16 v[54:57], v[182:185], v[200:203], 0
	v_mfma_f32_16x16x32_bf16 v[54:57], v[186:189], v[204:207], v[54:57]
	v_mfma_f32_16x16x32_bf16 v[58:61], v[174:177], v[200:203], 0
	v_mfma_f32_16x16x32_bf16 v[58:61], v[178:181], v[204:207], v[58:61]
	v_mfma_f32_16x16x32_bf16 v[62:65], v[158:161], v[200:203], 0
	v_mfma_f32_16x16x32_bf16 v[62:65], v[162:165], v[204:207], v[62:65]
	v_mfma_f32_16x16x32_bf16 v[66:69], v[150:153], v[200:203], 0
	v_mfma_f32_16x16x32_bf16 v[66:69], v[154:157], v[204:207], v[66:69]
	v_mfma_f32_16x16x32_bf16 v[42:45], v[150:153], v[208:211], 0
	v_mfma_f32_16x16x32_bf16 v[42:45], v[154:157], v[212:215], v[42:45]
	v_mfma_f32_16x16x32_bf16 v[34:37], v[158:161], v[208:211], 0
	v_mfma_f32_16x16x32_bf16 v[34:37], v[162:165], v[212:215], v[34:37]
	v_mfma_f32_16x16x32_bf16 v[26:29], v[174:177], v[208:211], 0
	v_mfma_f32_16x16x32_bf16 v[26:29], v[178:181], v[212:215], v[26:29]
	v_mfma_f32_16x16x32_bf16 v[22:25], v[182:185], v[208:211], 0
	v_mfma_f32_16x16x32_bf16 v[22:25], v[186:189], v[212:215], v[22:25]
	v_mfma_f32_16x16x32_bf16 v[4:7], v[182:185], v[220:223], 0
	v_mfma_f32_16x16x32_bf16 v[4:7], v[186:189], v[224:227], v[4:7]
	v_mfma_f32_16x16x32_bf16 v[10:13], v[174:177], v[220:223], 0
	v_mfma_f32_16x16x32_bf16 v[10:13], v[178:181], v[224:227], v[10:13]
	v_mfma_f32_16x16x32_bf16 v[14:17], v[158:161], v[220:223], 0
	v_mfma_f32_16x16x32_bf16 v[14:17], v[162:165], v[224:227], v[14:17]
	v_mfma_f32_16x16x32_bf16 v[18:21], v[150:153], v[220:223], 0
	v_mfma_f32_16x16x32_bf16 v[18:21], v[154:157], v[224:227], v[18:21]
	s_setprio 0
	s_waitcnt vmcnt(6)
	s_barrier
; #define PG8_STAGE(bufoff, gbase, voff) do { _Pragma("unroll") for (int _i = 0; _i < 2; ++_i) \
;         __builtin_amdgcn_global_load_lds((const unsigned*)((const char*)(gbase) + (voff)[_i]), (PG8_LAS unsigned*)(lds + (bufoff) + ldsw + _i * 8192), 16, 0, 0); } while (0)
; #define PG8_LDA(dst, b, h) do { _Pragma("unroll") for (int m = 0; m < 4; ++m) _Pragma("unroll") for (int k = 0; k < 2; ++k) dst[m][k] = *(const PG8_LAS bf16x8*)(lds + PG8_SA(b, h) + aoff + m * 2048 + k * 1024); } while (0)
; #define PG8_LDB(dst, b, h) do { _Pragma("unroll") for (int n = 0; n < 2; ++n) _Pragma("unroll") for (int k = 0; k < 2; ++k) dst[n][k] = *(const PG8_LAS bf16x8*)(lds + PG8_SB(b, h) + boff + n * 2048 + k * 1024); } while (0)
; #define PG8_MMA(ai, bj, At, Bt) do { __builtin_amdgcn_s_setprio(1); _Pragma("unroll") for (int m = 0; m < 4; ++m) _Pragma("unroll") for (int n = 0; n < 2; ++n) _Pragma("unroll") for (int k = 0; k < 2; ++k) \
;         acc[ai][bj][m][n] = __builtin_amdgcn_mfma_f32_16x16x32_bf16(Bt[n][k], At[m][k], acc[ai][bj][m][n], 0, 0, 0); __builtin_amdgcn_s_setprio(0); } while (0)
; #define PG8_WAIT_V(n) asm volatile("s_waitcnt vmcnt(" #n ")" ::: "memory")
; #define PG8_WAIT_L(n) asm volatile("s_waitcnt lgkmcnt(" #n ")" ::: "memory")
; #define PG8_BAR __builtin_amdgcn_s_barrier()
; #define PG8_SCHED __builtin_amdgcn_sched_barrier(0)
; template <class Epi, class Sched, bool ALIGN_EPI = false, bool SP2 = false>
; __device__ __forceinline__ void gemm_phase(PG8_LAS unsigned char* lds, const Gemm g, const Sched& S, const Epi& E) {
;     ...
;             PG8_LDB(B0, 1, 0); PG8_LDB(B1, 1, 1); PG8_SCHED; PG8_LDA(At, 1, 0); PG8_STAGE(PG8_SA(0, 1), a2 + hstep, voffA);
;             PG8_WAIT_V(8); PG8_WAIT_L(0); PG8_BAR; PG8_MMA(0, 0, At, B0); PG8_MMA(0, 1, At, B1); PG8_BAR; PG8_SCHED;
;             PG8_LDA(At, 1, 1); PG8_STAGE(PG8_SB(1, 0), b3, voffB); PG8_STAGE(PG8_SB(1, 1), b3 + hstep, voffB); PG8_STAGE(PG8_SA(1, 0), a3, voffA);
;             PG8_WAIT_V(8); PG8_WAIT_L(0); PG8_BAR; PG8_MMA(1, 0, At, B0); PG8_MMA(1, 1, At, B1); PG8_BAR; PG8_SCHED;
	s_add_i32 s0, 0, 0x18000
	v_add_u32_e32 v3, s0, v167
	s_add_i32 s1, 0, 0x1c000
	ds_read_b128 v[150:153], v3
	ds_read_b128 v[154:157], v3 offset:1024
	ds_read_b128 v[158:161], v3 offset:2048
	ds_read_b128 v[162:165], v3 offset:3072
	v_add_u32_e32 v3, s1, v167
	ds_read_b128 v[174:177], v3
	ds_read_b128 v[178:181], v3 offset:1024
	ds_read_b128 v[182:185], v3 offset:2048
	ds_read_b128 v[186:189], v3 offset:3072
	ds_read_b128 v[190:193], v171 offset:32768
	ds_read_b128 v[196:199], v171 offset:33792
	ds_read_b128 v[200:203], v171 offset:34816
	ds_read_b128 v[204:207], v171 offset:35840
	ds_read_b128 v[208:211], v171 offset:36864
	ds_read_b128 v[212:215], v171 offset:37888
	ds_read_b128 v[220:223], v171 offset:38912
	ds_read_b128 v[224:227], v171 offset:39936
	s_add_u32 vcc_lo, s92, 0x100000
	s_addc_u32 vcc_hi, s93, 0
	s_mov_b32 m0, s27
	s_nop 0
	global_load_lds_dwordx4 v134, s[92:93]
	s_add_i32 m0, s27, 0x2000
	s_nop 0
	global_load_lds_dwordx4 v138, s[92:93]
	s_add_i32 m0, s27, 0x4000
	s_nop 0
	global_load_lds_dwordx4 v134, vcc
	s_add_i32 m0, s27, 0x6000
	s_nop 0
	global_load_lds_dwordx4 v138, vcc
	s_waitcnt lgkmcnt(0)
	s_setprio 1
	v_mfma_f32_16x16x32_bf16 v[38:41], v[150:153], v[190:193], v[38:41]
	v_mfma_f32_16x16x32_bf16 v[38:41], v[154:157], v[196:199], v[38:41]
	v_mfma_f32_16x16x32_bf16 v[30:33], v[158:161], v[190:193], v[30:33]
	v_mfma_f32_16x16x32_bf16 v[30:33], v[162:165], v[196:199], v[30:33]
	v_mfma_f32_16x16x32_bf16 v[50:53], v[174:177], v[190:193], v[50:53]
	v_mfma_f32_16x16x32_bf16 v[50:53], v[178:181], v[196:199], v[50:53]
	v_mfma_f32_16x16x32_bf16 v[46:49], v[182:185], v[190:193], v[46:49]
	v_mfma_f32_16x16x32_bf16 v[46:49], v[186:189], v[196:199], v[46:49]
	v_mfma_f32_16x16x32_bf16 v[118:121], v[182:185], v[200:203], v[118:121]
	v_mfma_f32_16x16x32_bf16 v[118:121], v[186:189], v[204:207], v[118:121]
	v_mfma_f32_16x16x32_bf16 v[122:125], v[174:177], v[200:203], v[122:125]
	v_mfma_f32_16x16x32_bf16 v[122:125], v[178:181], v[204:207], v[122:125]
	v_mfma_f32_16x16x32_bf16 v[126:129], v[158:161], v[200:203], v[126:129]
	v_mfma_f32_16x16x32_bf16 v[126:129], v[162:165], v[204:207], v[126:129]
	v_mfma_f32_16x16x32_bf16 v[130:133], v[150:153], v[200:203], v[130:133]
	v_mfma_f32_16x16x32_bf16 v[130:133], v[154:157], v[204:207], v[130:133]
	v_mfma_f32_16x16x32_bf16 v[114:117], v[150:153], v[208:211], v[114:117]
	v_mfma_f32_16x16x32_bf16 v[114:117], v[154:157], v[212:215], v[114:117]
	v_mfma_f32_16x16x32_bf16 v[110:113], v[158:161], v[208:211], v[110:113]
	v_mfma_f32_16x16x32_bf16 v[110:113], v[162:165], v[212:215], v[110:113]
	v_mfma_f32_16x16x32_bf16 v[106:109], v[174:177], v[208:211], v[106:109]
	v_mfma_f32_16x16x32_bf16 v[106:109], v[178:181], v[212:215], v[106:109]
	v_mfma_f32_16x16x32_bf16 v[102:105], v[182:185], v[208:211], v[102:105]
	v_mfma_f32_16x16x32_bf16 v[102:105], v[186:189], v[212:215], v[102:105]
	v_mfma_f32_16x16x32_bf16 v[86:89], v[182:185], v[220:223], v[86:89]
	v_mfma_f32_16x16x32_bf16 v[86:89], v[186:189], v[224:227], v[86:89]
	v_mfma_f32_16x16x32_bf16 v[90:93], v[174:177], v[220:223], v[90:93]
	v_mfma_f32_16x16x32_bf16 v[90:93], v[178:181], v[224:227], v[90:93]
	v_mfma_f32_16x16x32_bf16 v[94:97], v[158:161], v[220:223], v[94:97]
	v_mfma_f32_16x16x32_bf16 v[94:97], v[162:165], v[224:227], v[94:97]
	v_mfma_f32_16x16x32_bf16 v[98:101], v[150:153], v[220:223], v[98:101]
	v_mfma_f32_16x16x32_bf16 v[98:101], v[154:157], v[224:227], v[98:101]
	s_setprio 0
	s_waitcnt vmcnt(8)
	s_barrier
	ds_read_b128 v[190:193], v171 offset:49152
	ds_read_b128 v[196:199], v171 offset:50176
	ds_read_b128 v[200:203], v171 offset:51200
	ds_read_b128 v[204:207], v171 offset:52224
	ds_read_b128 v[208:211], v171 offset:53248
	ds_read_b128 v[212:215], v171 offset:54272
	ds_read_b128 v[220:223], v171 offset:55296
	ds_read_b128 v[224:227], v171 offset:56320
	s_add_u32 s0, s90, 0x80
	s_addc_u32 s1, s91, 0
	s_add_u32 vcc_lo, s0, 0x100000
	s_addc_u32 vcc_hi, s1, 0
	s_add_i32 m0, s27, 0x18000
	s_nop 0
	global_load_lds_dwordx4 v136, s[0:1]
	s_add_i32 m0, s27, 0x1a000
	s_nop 0
	global_load_lds_dwordx4 v140, s[0:1]
	s_add_i32 m0, s27, 0x1c000
	s_nop 0
	global_load_lds_dwordx4 v136, vcc
	s_add_i32 m0, s27, 0x1e000
	s_nop 0
	global_load_lds_dwordx4 v140, vcc
	s_waitcnt lgkmcnt(0)
	s_setprio 1
	v_mfma_f32_16x16x32_bf16 v[70:73], v[182:185], v[190:193], v[70:73]
	v_mfma_f32_16x16x32_bf16 v[70:73], v[186:189], v[196:199], v[70:73]
	v_mfma_f32_16x16x32_bf16 v[74:77], v[174:177], v[190:193], v[74:77]
	v_mfma_f32_16x16x32_bf16 v[74:77], v[178:181], v[196:199], v[74:77]
	v_mfma_f32_16x16x32_bf16 v[78:81], v[158:161], v[190:193], v[78:81]
	v_mfma_f32_16x16x32_bf16 v[78:81], v[162:165], v[196:199], v[78:81]
	v_mfma_f32_16x16x32_bf16 v[82:85], v[150:153], v[190:193], v[82:85]
	v_mfma_f32_16x16x32_bf16 v[82:85], v[154:157], v[196:199], v[82:85]
	v_mfma_f32_16x16x32_bf16 v[66:69], v[150:153], v[200:203], v[66:69]
	v_mfma_f32_16x16x32_bf16 v[66:69], v[154:157], v[204:207], v[66:69]
	v_mfma_f32_16x16x32_bf16 v[62:65], v[158:161], v[200:203], v[62:65]
	v_mfma_f32_16x16x32_bf16 v[62:65], v[162:165], v[204:207], v[62:65]
	v_mfma_f32_16x16x32_bf16 v[58:61], v[174:177], v[200:203], v[58:61]
	v_mfma_f32_16x16x32_bf16 v[58:61], v[178:181], v[204:207], v[58:61]
	v_mfma_f32_16x16x32_bf16 v[54:57], v[182:185], v[200:203], v[54:57]
	v_mfma_f32_16x16x32_bf16 v[54:57], v[186:189], v[204:207], v[54:57]
	v_mfma_f32_16x16x32_bf16 v[22:25], v[182:185], v[208:211], v[22:25]
	v_mfma_f32_16x16x32_bf16 v[22:25], v[186:189], v[212:215], v[22:25]
	v_mfma_f32_16x16x32_bf16 v[26:29], v[174:177], v[208:211], v[26:29]
	v_mfma_f32_16x16x32_bf16 v[26:29], v[178:181], v[212:215], v[26:29]
	v_mfma_f32_16x16x32_bf16 v[34:37], v[158:161], v[208:211], v[34:37]
	v_mfma_f32_16x16x32_bf16 v[34:37], v[162:165], v[212:215], v[34:37]
	v_mfma_f32_16x16x32_bf16 v[42:45], v[150:153], v[208:211], v[42:45]
	v_mfma_f32_16x16x32_bf16 v[42:45], v[154:157], v[212:215], v[42:45]
	v_mfma_f32_16x16x32_bf16 v[18:21], v[150:153], v[220:223], v[18:21]
	v_mfma_f32_16x16x32_bf16 v[18:21], v[154:157], v[224:227], v[18:21]
	v_mfma_f32_16x16x32_bf16 v[14:17], v[158:161], v[220:223], v[14:17]
	v_mfma_f32_16x16x32_bf16 v[14:17], v[162:165], v[224:227], v[14:17]
	v_mfma_f32_16x16x32_bf16 v[8:11], v[174:177], v[220:223], v[10:13]
	v_mfma_f32_16x16x32_bf16 v[10:13], v[178:181], v[224:227], v[8:11]
	v_mfma_f32_16x16x32_bf16 v[4:7], v[182:185], v[220:223], v[4:7]
	v_mfma_f32_16x16x32_bf16 v[6:9], v[186:189], v[224:227], v[4:7]
	s_setprio 0
	s_waitcnt vmcnt(6)
	s_barrier
	s_add_i32 s23, s23, 2
	s_add_u32 s88, s88, 0x100
	s_addc_u32 s89, s89, 0
	s_add_u32 s9, s9, 0x100
	s_addc_u32 s21, s21, 0
	s_cmp_gt_u32 s23, 61

; #define PG8_STAGE(bufoff, gbase, voff) do { _Pragma("unroll") for (int _i = 0; _i < 2; ++_i) \
;         __builtin_amdgcn_global_load_lds((const unsigned*)((const char*)(gbase) + (voff)[_i]), (PG8_LAS unsigned*)(lds + (bufoff) + ldsw + _i * 8192), 16, 0, 0); } while (0)
; #define PG8_LDA(dst, b, h) do { _Pragma("unroll") for (int m = 0; m < 4; ++m) _Pragma("unroll") for (int k = 0; k < 2; ++k) dst[m][k] = *(const PG8_LAS bf16x8*)(lds + PG8_SA(b, h) + aoff + m * 2048 + k * 1024); } while (0)
; #define PG8_LDB(dst, b, h) do { _Pragma("unroll") for (int n = 0; n < 2; ++n) _Pragma("unroll") for (int k = 0; k < 2; ++k) dst[n][k] = *(const PG8_LAS bf16x8*)(lds + PG8_SB(b, h) + boff + n * 2048 + k * 1024); } while (0)
; #define PG8_MMA(ai, bj, At, Bt) do { __builtin_amdgcn_s_setprio(1); _Pragma("unroll") for (int m = 0; m < 4; ++m) _Pragma("unroll") for (int n = 0; n < 2; ++n) _Pragma("unroll") for (int k = 0; k < 2; ++k) \
;         acc[ai][bj][m][n] = __builtin_amdgcn_mfma_f32_16x16x32_bf16(Bt[n][k], At[m][k], acc[ai][bj][m][n], 0, 0, 0); __builtin_amdgcn_s_setprio(0); } while (0)
; #define PG8_WAIT_V(n) asm volatile("s_waitcnt vmcnt(" #n ")" ::: "memory")
; #define PG8_WAIT_L(n) asm volatile("s_waitcnt lgkmcnt(" #n ")" ::: "memory")
; #define PG8_BAR __builtin_amdgcn_s_barrier()
; #define PG8_SCHED __builtin_amdgcn_sched_barrier(0)
; template <class Epi, class Sched, bool ALIGN_EPI = false, bool SP2 = false>
; __device__ __forceinline__ void gemm_phase(PG8_LAS unsigned char* lds, const Gemm g, const Sched& S, const Epi& E) {
;     ...
;             PG8_LDB(B0, 0, 0); PG8_LDB(B1, 0, 1); PG8_SCHED; PG8_LDA(At, 0, 0); PG8_STAGE(PG8_SA(1, 1), a1 + hstep, voffA);
;             PG8_WAIT_V(8); PG8_WAIT_L(0); PG8_BAR; PG8_MMA(0, 0, At, B0); PG8_MMA(0, 1, At, B1); PG8_BAR; PG8_SCHED;
;             PG8_LDA(At, 0, 1); PG8_STAGE(PG8_SB(0, 0), b2, voffB); PG8_STAGE(PG8_SB(0, 1), b2 + hstep, voffB); PG8_STAGE(PG8_SA(0, 0), a2, voffA);
;             PG8_WAIT_V(8); PG8_WAIT_L(0); PG8_BAR; PG8_MMA(1, 0, At, B0); PG8_MMA(1, 1, At, B1); PG8_BAR; PG8_SCHED;
.Lip_h1first:
	ds_read_b128 v[150:153], v169
	ds_read_b128 v[154:157], v169 offset:1024
	ds_read_b128 v[158:161], v169 offset:2048
	ds_read_b128 v[162:165], v169 offset:3072
	ds_read_b128 v[174:177], v170
	ds_read_b128 v[178:181], v170 offset:1024
	ds_read_b128 v[182:185], v170 offset:2048
	ds_read_b128 v[186:189], v170 offset:3072
	s_add_u32 s0, s88, 0xfff00080
	s_addc_u32 s1, s89, -1
	s_cmp_eq_u32 s23, 60
	s_cselect_b32 s93, s51, s1
	s_cselect_b32 s92, s50, s0
	s_cselect_b32 s91, s53, s21
	s_cselect_b32 s90, s52, s9
	ds_read_b128 v[190:193], v171
	ds_read_b128 v[196:199], v171 offset:1024
	ds_read_b128 v[200:203], v171 offset:2048
	ds_read_b128 v[204:207], v171 offset:3072
	ds_read_b128 v[208:211], v171 offset:4096
	ds_read_b128 v[212:215], v171 offset:5120
	ds_read_b128 v[220:223], v171 offset:6144
	ds_read_b128 v[224:227], v171 offset:7168
	s_add_u32 s0, s88, 0xfff00000
	s_addc_u32 s1, s89, -1
	s_add_i32 m0, s27, 0x8000
	s_nop 0
	global_load_lds_dwordx4 v134, s[0:1]
	s_add_i32 m0, s27, 0xa000
	s_nop 0
	global_load_lds_dwordx4 v138, s[0:1]
	s_add_i32 m0, s27, 0xc000
	s_nop 0
	global_load_lds_dwordx4 v134, s[88:89]
	s_add_i32 m0, s27, 0xe000
	s_nop 0
	global_load_lds_dwordx4 v138, s[88:89]
	s_sleep 2
	s_waitcnt lgkmcnt(0)
	s_waitcnt vmcnt(8)
	s_barrier
	s_setprio 2
	v_mfma_f32_16x16x32_bf16 v[38:41], v[150:153], v[190:193], 0
	v_mfma_f32_16x16x32_bf16 v[38:41], v[154:157], v[196:199], v[38:41]
	v_mfma_f32_16x16x32_bf16 v[30:33], v[158:161], v[190:193], 0
	v_mfma_f32_16x16x32_bf16 v[30:33], v[162:165], v[196:199], v[30:33]
	v_mfma_f32_16x16x32_bf16 v[50:53], v[174:177], v[190:193], 0
	v_mfma_f32_16x16x32_bf16 v[50:53], v[178:181], v[196:199], v[50:53]
	v_mfma_f32_16x16x32_bf16 v[46:49], v[182:185], v[190:193], 0
	v_mfma_f32_16x16x32_bf16 v[46:49], v[186:189], v[196:199], v[46:49]
	v_mfma_f32_16x16x32_bf16 v[118:121], v[182:185], v[200:203], 0
	v_mfma_f32_16x16x32_bf16 v[118:121], v[186:189], v[204:207], v[118:121]
	v_mfma_f32_16x16x32_bf16 v[122:125], v[174:177], v[200:203], 0
	v_mfma_f32_16x16x32_bf16 v[122:125], v[178:181], v[204:207], v[122:125]
	v_mfma_f32_16x16x32_bf16 v[126:129], v[158:161], v[200:203], 0
	v_mfma_f32_16x16x32_bf16 v[126:129], v[162:165], v[204:207], v[126:129]
	v_mfma_f32_16x16x32_bf16 v[130:133], v[150:153], v[200:203], 0
	v_mfma_f32_16x16x32_bf16 v[130:133], v[154:157], v[204:207], v[130:133]
	v_mfma_f32_16x16x32_bf16 v[114:117], v[150:153], v[208:211], 0
	v_mfma_f32_16x16x32_bf16 v[114:117], v[154:157], v[212:215], v[114:117]
	v_mfma_f32_16x16x32_bf16 v[110:113], v[158:161], v[208:211], 0
	v_mfma_f32_16x16x32_bf16 v[110:113], v[162:165], v[212:215], v[110:113]
	v_mfma_f32_16x16x32_bf16 v[106:109], v[174:177], v[208:211], 0
	v_mfma_f32_16x16x32_bf16 v[106:109], v[178:181], v[212:215], v[106:109]
	v_mfma_f32_16x16x32_bf16 v[102:105], v[182:185], v[208:211], 0
	v_mfma_f32_16x16x32_bf16 v[102:105], v[186:189], v[212:215], v[102:105]
	v_mfma_f32_16x16x32_bf16 v[86:89], v[182:185], v[220:223], 0
	v_mfma_f32_16x16x32_bf16 v[86:89], v[186:189], v[224:227], v[86:89]
	v_mfma_f32_16x16x32_bf16 v[90:93], v[174:177], v[220:223], 0
	v_mfma_f32_16x16x32_bf16 v[90:93], v[178:181], v[224:227], v[90:93]
	v_mfma_f32_16x16x32_bf16 v[94:97], v[158:161], v[220:223], 0
	v_mfma_f32_16x16x32_bf16 v[94:97], v[162:165], v[224:227], v[94:97]
	v_mfma_f32_16x16x32_bf16 v[98:101], v[150:153], v[220:223], 0
	v_mfma_f32_16x16x32_bf16 v[98:101], v[154:157], v[224:227], v[98:101]
	s_setprio 0
	ds_read_b128 v[190:193], v171 offset:16384
	ds_read_b128 v[196:199], v171 offset:17408
	ds_read_b128 v[200:203], v171 offset:18432
	ds_read_b128 v[204:207], v171 offset:19456
	ds_read_b128 v[208:211], v171 offset:20480
	ds_read_b128 v[212:215], v171 offset:21504
	ds_read_b128 v[220:223], v171 offset:22528
	ds_read_b128 v[224:227], v171 offset:23552
	s_add_u32 vcc_lo, s90, 0x100000
	s_addc_u32 vcc_hi, s91, 0
	s_add_i32 m0, s27, 0x10000
	s_nop 0
	global_load_lds_dwordx4 v136, s[90:91]
	s_add_i32 m0, s27, 0x12000
	s_nop 0
	global_load_lds_dwordx4 v140, s[90:91]
	s_add_i32 m0, s27, 0x14000
	s_nop 0
	global_load_lds_dwordx4 v136, vcc
	s_add_i32 m0, s27, 0x16000
	s_nop 0
	global_load_lds_dwordx4 v140, vcc
	s_sleep 2
	s_waitcnt lgkmcnt(0)
	s_waitcnt vmcnt(6)
	s_barrier
	s_setprio 2
	v_mfma_f32_16x16x32_bf16 v[82:85], v[150:153], v[190:193], 0
	v_mfma_f32_16x16x32_bf16 v[82:85], v[154:157], v[196:199], v[82:85]
	v_mfma_f32_16x16x32_bf16 v[78:81], v[158:161], v[190:193], 0
	v_mfma_f32_16x16x32_bf16 v[78:81], v[162:165], v[196:199], v[78:81]
	v_mfma_f32_16x16x32_bf16 v[74:77], v[174:177], v[190:193], 0
	v_mfma_f32_16x16x32_bf16 v[74:77], v[178:181], v[196:199], v[74:77]
	v_mfma_f32_16x16x32_bf16 v[70:73], v[182:185], v[190:193], 0
	v_mfma_f32_16x16x32_bf16 v[70:73], v[186:189], v[196:199], v[70:73]
	v_mfma_f32_16x16x32_bf16 v[54:57], v[182:185], v[200:203], 0
	v_mfma_f32_16x16x32_bf16 v[54:57], v[186:189], v[204:207], v[54:57]
	v_mfma_f32_16x16x32_bf16 v[58:61], v[174:177], v[200:203], 0
	v_mfma_f32_16x16x32_bf16 v[58:61], v[178:181], v[204:207], v[58:61]
	v_mfma_f32_16x16x32_bf16 v[62:65], v[158:161], v[200:203], 0
	v_mfma_f32_16x16x32_bf16 v[62:65], v[162:165], v[204:207], v[62:65]
	v_mfma_f32_16x16x32_bf16 v[66:69], v[150:153], v[200:203], 0
	v_mfma_f32_16x16x32_bf16 v[66:69], v[154:157], v[204:207], v[66:69]
	v_mfma_f32_16x16x32_bf16 v[42:45], v[150:153], v[208:211], 0
	v_mfma_f32_16x16x32_bf16 v[42:45], v[154:157], v[212:215], v[42:45]
	v_mfma_f32_16x16x32_bf16 v[34:37], v[158:161], v[208:211], 0
	v_mfma_f32_16x16x32_bf16 v[34:37], v[162:165], v[212:215], v[34:37]
	v_mfma_f32_16x16x32_bf16 v[26:29], v[174:177], v[208:211], 0
; #define PG8_STAGE(bufoff, gbase, voff) do { _Pragma("unroll") for (int _i = 0; _i < 2; ++_i) \
;         __builtin_amdgcn_global_load_lds((const unsigned*)((const char*)(gbase) + (voff)[_i]), (PG8_LAS unsigned*)(lds + (bufoff) + ldsw + _i * 8192), 16, 0, 0); } while (0)
; #define PG8_LDA(dst, b, h) do { _Pragma("unroll") for (int m = 0; m < 4; ++m) _Pragma("unroll") for (int k = 0; k < 2; ++k) dst[m][k] = *(const PG8_LAS bf16x8*)(lds + PG8_SA(b, h) + aoff + m * 2048 + k * 1024); } while (0)
; #define PG8_LDB(dst, b, h) do { _Pragma("unroll") for (int n = 0; n < 2; ++n) _Pragma("unroll") for (int k = 0; k < 2; ++k) dst[n][k] = *(const PG8_LAS bf16x8*)(lds + PG8_SB(b, h) + boff + n * 2048 + k * 1024); } while (0)
; #define PG8_MMA(ai, bj, At, Bt) do { __builtin_amdgcn_s_setprio(1); _Pragma("unroll") for (int m = 0; m < 4; ++m) _Pragma("unroll") for (int n = 0; n < 2; ++n) _Pragma("unroll") for (int k = 0; k < 2; ++k) \
;         acc[ai][bj][m][n] = __builtin_amdgcn_mfma_f32_16x16x32_bf16(Bt[n][k], At[m][k], acc[ai][bj][m][n], 0, 0, 0); __builtin_amdgcn_s_setprio(0); } while (0)
; #define PG8_WAIT_V(n) asm volatile("s_waitcnt vmcnt(" #n ")" ::: "memory")
; #define PG8_WAIT_L(n) asm volatile("s_waitcnt lgkmcnt(" #n ")" ::: "memory")
; #define PG8_BAR __builtin_amdgcn_s_barrier()
; #define PG8_SCHED __builtin_amdgcn_sched_barrier(0)
; template <class Epi, class Sched, bool ALIGN_EPI = false, bool SP2 = false>
; __device__ __forceinline__ void gemm_phase(PG8_LAS unsigned char* lds, const Gemm g, const Sched& S, const Epi& E) {
;     ...
;             PG8_WAIT_V(8); PG8_WAIT_L(0); PG8_BAR; PG8_MMA(1, 0, At, B0); PG8_MMA(1, 1, At, B1); PG8_BAR; PG8_SCHED;
;             PG8_LDB(B0, 1, 0); PG8_LDB(B1, 1, 1); PG8_SCHED; PG8_LDA(At, 1, 0); PG8_STAGE(PG8_SA(0, 1), a2 + hstep, voffA);
;             PG8_WAIT_V(8); PG8_WAIT_L(0); PG8_BAR; PG8_MMA(0, 0, At, B0); PG8_MMA(0, 1, At, B1); PG8_BAR; PG8_SCHED;
;             PG8_LDA(At, 1, 1); PG8_STAGE(PG8_SB(1, 0), b3, voffB); PG8_STAGE(PG8_SB(1, 1), b3 + hstep, voffB); PG8_STAGE(PG8_SA(1, 0), a3, voffA);
	v_mfma_f32_16x16x32_bf16 v[26:29], v[178:181], v[212:215], v[26:29]
	v_mfma_f32_16x16x32_bf16 v[22:25], v[182:185], v[208:211], 0
	v_mfma_f32_16x16x32_bf16 v[22:25], v[186:189], v[212:215], v[22:25]
	v_mfma_f32_16x16x32_bf16 v[4:7], v[182:185], v[220:223], 0
	v_mfma_f32_16x16x32_bf16 v[4:7], v[186:189], v[224:227], v[4:7]
	v_mfma_f32_16x16x32_bf16 v[10:13], v[174:177], v[220:223], 0
	v_mfma_f32_16x16x32_bf16 v[10:13], v[178:181], v[224:227], v[10:13]
	v_mfma_f32_16x16x32_bf16 v[14:17], v[158:161], v[220:223], 0
	v_mfma_f32_16x16x32_bf16 v[14:17], v[162:165], v[224:227], v[14:17]
	v_mfma_f32_16x16x32_bf16 v[18:21], v[150:153], v[220:223], 0
	v_mfma_f32_16x16x32_bf16 v[18:21], v[154:157], v[224:227], v[18:21]
	s_setprio 0
	s_add_i32 s0, 0, 0x18000
	v_add_u32_e32 v3, s0, v167
	s_add_i32 s1, 0, 0x1c000
	ds_read_b128 v[150:153], v3
	ds_read_b128 v[154:157], v3 offset:1024
	ds_read_b128 v[158:161], v3 offset:2048
	ds_read_b128 v[162:165], v3 offset:3072
	v_add_u32_e32 v3, s1, v167
	ds_read_b128 v[174:177], v3
	ds_read_b128 v[178:181], v3 offset:1024
	ds_read_b128 v[182:185], v3 offset:2048
	ds_read_b128 v[186:189], v3 offset:3072
	ds_read_b128 v[190:193], v171 offset:32768
	ds_read_b128 v[196:199], v171 offset:33792
	ds_read_b128 v[200:203], v171 offset:34816
	ds_read_b128 v[204:207], v171 offset:35840
	ds_read_b128 v[208:211], v171 offset:36864
	ds_read_b128 v[212:215], v171 offset:37888
	ds_read_b128 v[220:223], v171 offset:38912
	ds_read_b128 v[224:227], v171 offset:39936
	s_add_u32 vcc_lo, s92, 0x100000
	s_addc_u32 vcc_hi, s93, 0
	s_mov_b32 m0, s27
	s_nop 0
	global_load_lds_dwordx4 v134, s[92:93]
	s_add_i32 m0, s27, 0x2000
	s_nop 0
	global_load_lds_dwordx4 v138, s[92:93]
	s_add_i32 m0, s27, 0x4000
	s_nop 0
	global_load_lds_dwordx4 v134, vcc
	s_add_i32 m0, s27, 0x6000
	s_nop 0
	global_load_lds_dwordx4 v138, vcc
	s_sleep 2
	s_waitcnt lgkmcnt(0)
	s_waitcnt vmcnt(8)
	s_barrier
	s_setprio 2
	v_mfma_f32_16x16x32_bf16 v[38:41], v[150:153], v[190:193], v[38:41]
	v_mfma_f32_16x16x32_bf16 v[38:41], v[154:157], v[196:199], v[38:41]
	v_mfma_f32_16x16x32_bf16 v[30:33], v[158:161], v[190:193], v[30:33]
	v_mfma_f32_16x16x32_bf16 v[30:33], v[162:165], v[196:199], v[30:33]
	v_mfma_f32_16x16x32_bf16 v[50:53], v[174:177], v[190:193], v[50:53]
	v_mfma_f32_16x16x32_bf16 v[50:53], v[178:181], v[196:199], v[50:53]
	v_mfma_f32_16x16x32_bf16 v[46:49], v[182:185], v[190:193], v[46:49]
	v_mfma_f32_16x16x32_bf16 v[46:49], v[186:189], v[196:199], v[46:49]
	v_mfma_f32_16x16x32_bf16 v[118:121], v[182:185], v[200:203], v[118:121]
	v_mfma_f32_16x16x32_bf16 v[118:121], v[186:189], v[204:207], v[118:121]
	v_mfma_f32_16x16x32_bf16 v[122:125], v[174:177], v[200:203], v[122:125]
	v_mfma_f32_16x16x32_bf16 v[122:125], v[178:181], v[204:207], v[122:125]
	v_mfma_f32_16x16x32_bf16 v[126:129], v[158:161], v[200:203], v[126:129]
	v_mfma_f32_16x16x32_bf16 v[126:129], v[162:165], v[204:207], v[126:129]
	v_mfma_f32_16x16x32_bf16 v[130:133], v[150:153], v[200:203], v[130:133]
	v_mfma_f32_16x16x32_bf16 v[130:133], v[154:157], v[204:207], v[130:133]
	v_mfma_f32_16x16x32_bf16 v[114:117], v[150:153], v[208:211], v[114:117]
	v_mfma_f32_16x16x32_bf16 v[114:117], v[154:157], v[212:215], v[114:117]
	v_mfma_f32_16x16x32_bf16 v[110:113], v[158:161], v[208:211], v[110:113]
	v_mfma_f32_16x16x32_bf16 v[110:113], v[162:165], v[212:215], v[110:113]
	v_mfma_f32_16x16x32_bf16 v[106:109], v[174:177], v[208:211], v[106:109]
	v_mfma_f32_16x16x32_bf16 v[106:109], v[178:181], v[212:215], v[106:109]
	v_mfma_f32_16x16x32_bf16 v[102:105], v[182:185], v[208:211], v[102:105]
	v_mfma_f32_16x16x32_bf16 v[102:105], v[186:189], v[212:215], v[102:105]
	v_mfma_f32_16x16x32_bf16 v[86:89], v[182:185], v[220:223], v[86:89]
	v_mfma_f32_16x16x32_bf16 v[86:89], v[186:189], v[224:227], v[86:89]
	v_mfma_f32_16x16x32_bf16 v[90:93], v[174:177], v[220:223], v[90:93]
	v_mfma_f32_16x16x32_bf16 v[90:93], v[178:181], v[224:227], v[90:93]
	v_mfma_f32_16x16x32_bf16 v[94:97], v[158:161], v[220:223], v[94:97]
	v_mfma_f32_16x16x32_bf16 v[94:97], v[162:165], v[224:227], v[94:97]
	v_mfma_f32_16x16x32_bf16 v[98:101], v[150:153], v[220:223], v[98:101]
	v_mfma_f32_16x16x32_bf16 v[98:101], v[154:157], v[224:227], v[98:101]
	s_setprio 0
	ds_read_b128 v[190:193], v171 offset:49152
	ds_read_b128 v[196:199], v171 offset:50176
	ds_read_b128 v[200:203], v171 offset:51200
	ds_read_b128 v[204:207], v171 offset:52224
	ds_read_b128 v[208:211], v171 offset:53248
	ds_read_b128 v[212:215], v171 offset:54272
	ds_read_b128 v[220:223], v171 offset:55296
	ds_read_b128 v[224:227], v171 offset:56320
	s_add_u32 s0, s90, 0x80
	s_addc_u32 s1, s91, 0
	s_add_u32 vcc_lo, s0, 0x100000
	s_addc_u32 vcc_hi, s1, 0
	s_add_i32 m0, s27, 0x18000
	s_nop 0
	global_load_lds_dwordx4 v136, s[0:1]
	s_add_i32 m0, s27, 0x1a000
	s_nop 0
	global_load_lds_dwordx4 v140, s[0:1]
	s_add_i32 m0, s27, 0x1c000
	s_nop 0
	global_load_lds_dwordx4 v136, vcc
	s_add_i32 m0, s27, 0x1e000
	s_nop 0
	global_load_lds_dwordx4 v140, vcc
	s_sleep 2
	s_waitcnt lgkmcnt(0)
	s_waitcnt vmcnt(6)
	s_barrier
; #define PG8_STAGE(bufoff, gbase, voff) do { _Pragma("unroll") for (int _i = 0; _i < 2; ++_i) \
;         __builtin_amdgcn_global_load_lds((const unsigned*)((const char*)(gbase) + (voff)[_i]), (PG8_LAS unsigned*)(lds + (bufoff) + ldsw + _i * 8192), 16, 0, 0); } while (0)
; #define PG8_LDA(dst, b, h) do { _Pragma("unroll") for (int m = 0; m < 4; ++m) _Pragma("unroll") for (int k = 0; k < 2; ++k) dst[m][k] = *(const PG8_LAS bf16x8*)(lds + PG8_SA(b, h) + aoff + m * 2048 + k * 1024); } while (0)
; #define PG8_MMA(ai, bj, At, Bt) do { __builtin_amdgcn_s_setprio(1); _Pragma("unroll") for (int m = 0; m < 4; ++m) _Pragma("unroll") for (int n = 0; n < 2; ++n) _Pragma("unroll") for (int k = 0; k < 2; ++k) \
;         acc[ai][bj][m][n] = __builtin_amdgcn_mfma_f32_16x16x32_bf16(Bt[n][k], At[m][k], acc[ai][bj][m][n], 0, 0, 0); __builtin_amdgcn_s_setprio(0); } while (0)
; #define PG8_WAIT_V(n) asm volatile("s_waitcnt vmcnt(" #n ")" ::: "memory")
; #define PG8_WAIT_L(n) asm volatile("s_waitcnt lgkmcnt(" #n ")" ::: "memory")
; #define PG8_BAR __builtin_amdgcn_s_barrier()
; #define PG8_SCHED __builtin_amdgcn_sched_barrier(0)
; template <class Epi, class Sched, bool ALIGN_EPI = false, bool SP2 = false>
; __device__ __forceinline__ void gemm_phase(PG8_LAS unsigned char* lds, const Gemm g, const Sched& S, const Epi& E) {
;     ...
;         for (int t = 0; t < nt; t += 2) {
;             const bool last = (t == nt - 2);
;             const char* a1 = cA + (size_t)(t + 1) * kstep;
;             const char* a2 = last ? nA : cA + (size_t)(t + 2) * kstep; const char* b2 = last ? nB : cB + (size_t)(t + 2) * kstep;
;             const char* a3 = a2 + kstep; const char* b3 = b2 + kstep;
;     ...
;             PG8_LDA(At, 1, 1); PG8_STAGE(PG8_SB(1, 0), b3, voffB); PG8_STAGE(PG8_SB(1, 1), b3 + hstep, voffB); PG8_STAGE(PG8_SA(1, 0), a3, voffA);
;             PG8_WAIT_V(8); PG8_WAIT_L(0); PG8_BAR; PG8_MMA(1, 0, At, B0); PG8_MMA(1, 1, At, B1); PG8_BAR; PG8_SCHED;
	s_setprio 2
	v_mfma_f32_16x16x32_bf16 v[70:73], v[182:185], v[190:193], v[70:73]
	v_mfma_f32_16x16x32_bf16 v[70:73], v[186:189], v[196:199], v[70:73]
	v_mfma_f32_16x16x32_bf16 v[74:77], v[174:177], v[190:193], v[74:77]
	v_mfma_f32_16x16x32_bf16 v[74:77], v[178:181], v[196:199], v[74:77]
	v_mfma_f32_16x16x32_bf16 v[78:81], v[158:161], v[190:193], v[78:81]
	v_mfma_f32_16x16x32_bf16 v[78:81], v[162:165], v[196:199], v[78:81]
	v_mfma_f32_16x16x32_bf16 v[82:85], v[150:153], v[190:193], v[82:85]
	v_mfma_f32_16x16x32_bf16 v[82:85], v[154:157], v[196:199], v[82:85]
	v_mfma_f32_16x16x32_bf16 v[66:69], v[150:153], v[200:203], v[66:69]
	v_mfma_f32_16x16x32_bf16 v[66:69], v[154:157], v[204:207], v[66:69]
	v_mfma_f32_16x16x32_bf16 v[62:65], v[158:161], v[200:203], v[62:65]
	v_mfma_f32_16x16x32_bf16 v[62:65], v[162:165], v[204:207], v[62:65]
	v_mfma_f32_16x16x32_bf16 v[58:61], v[174:177], v[200:203], v[58:61]
	v_mfma_f32_16x16x32_bf16 v[58:61], v[178:181], v[204:207], v[58:61]
	v_mfma_f32_16x16x32_bf16 v[54:57], v[182:185], v[200:203], v[54:57]
	v_mfma_f32_16x16x32_bf16 v[54:57], v[186:189], v[204:207], v[54:57]
	v_mfma_f32_16x16x32_bf16 v[22:25], v[182:185], v[208:211], v[22:25]
	v_mfma_f32_16x16x32_bf16 v[22:25], v[186:189], v[212:215], v[22:25]
	v_mfma_f32_16x16x32_bf16 v[26:29], v[174:177], v[208:211], v[26:29]
	v_mfma_f32_16x16x32_bf16 v[26:29], v[178:181], v[212:215], v[26:29]
	v_mfma_f32_16x16x32_bf16 v[34:37], v[158:161], v[208:211], v[34:37]
	v_mfma_f32_16x16x32_bf16 v[34:37], v[162:165], v[212:215], v[34:37]
	v_mfma_f32_16x16x32_bf16 v[42:45], v[150:153], v[208:211], v[42:45]
	v_mfma_f32_16x16x32_bf16 v[42:45], v[154:157], v[212:215], v[42:45]
	v_mfma_f32_16x16x32_bf16 v[18:21], v[150:153], v[220:223], v[18:21]
	v_mfma_f32_16x16x32_bf16 v[18:21], v[154:157], v[224:227], v[18:21]
	v_mfma_f32_16x16x32_bf16 v[14:17], v[158:161], v[220:223], v[14:17]
	v_mfma_f32_16x16x32_bf16 v[14:17], v[162:165], v[224:227], v[14:17]
	v_mfma_f32_16x16x32_bf16 v[8:11], v[174:177], v[220:223], v[10:13]
	v_mfma_f32_16x16x32_bf16 v[10:13], v[178:181], v[224:227], v[8:11]
	v_mfma_f32_16x16x32_bf16 v[4:7], v[182:185], v[220:223], v[4:7]
	v_mfma_f32_16x16x32_bf16 v[6:9], v[186:189], v[224:227], v[4:7]
	s_setprio 0
	s_add_i32 s23, s23, 2
	s_add_u32 s88, s88, 0x100
	s_addc_u32 s89, s89, 0
	s_add_u32 s9, s9, 0x100
	s_addc_u32 s21, s21, 0
	s_cmp_gt_u32 s23, 61

;     __device__ __forceinline__ bool next(int i, Unit& u) const { const long L = (long)i * G + c; if (L >= nwg) return false; std_map((int)L, nM, nN, u, wgm); u.ui = i; return true; }
;     __device__ __forceinline__ bool next(int i, Unit& u) const { if (i >= 4) return false; const int x = c & 7, r = c >> 3; u.pm = 16 * i + 4 * (x >> 1) + (r & 3); u.pn = 8 * (x & 1) + (r >> 2); u.ui = i; return true; }
; #define PG8_STAGE(bufoff, gbase, voff) do { _Pragma("unroll") for (int _i = 0; _i < 2; ++_i) \
;         __builtin_amdgcn_global_load_lds((const unsigned*)((const char*)(gbase) + (voff)[_i]), (PG8_LAS unsigned*)(lds + (bufoff) + ldsw + _i * 8192), 16, 0, 0); } while (0)
; template <class Epi, class Sched, bool ALIGN_EPI = false, bool SP2 = false>
; __device__ __forceinline__ void gemm_phase(PG8_LAS unsigned char* lds, const Gemm g, const Sched& S, const Epi& E) {
;     ...
;         const bool has_next = S.next(ui + 1, nxt);
;         const char* nA = cA; const char* nB = cB; if (has_next) S.bases(nxt, g, tstep, nA, nB);
;         for (int t = 0; t < nt; t += 2) {
;             const bool last = (t == nt - 2);
;             const char* a1 = cA + (size_t)(t + 1) * kstep;
;             const char* a2 = last ? nA : cA + (size_t)(t + 2) * kstep; const char* b2 = last ? nB : cB + (size_t)(t + 2) * kstep;
;             const char* a3 = a2 + kstep; const char* b3 = b2 + kstep;
;             if (last && has_next) S.a_ready(nxt);
;             if constexpr (Epi::MIDK) { if (t == (nt >> 1)) { E.midk(acc, wr, fr); asm volatile("s_waitcnt lgkmcnt(0)" ::: "memory"); } }
;             if constexpr (SP2) {
;             PG8_LDB(B0, 0, 0); PG8_LDB(B1, 0, 1); PG8_SCHED; PG8_LDA(At, 0, 0); PG8_STAGE(PG8_SA(1, 1), a1 + hstep, voffA);
;             PG8_WAIT_V(8); PG8_WAIT_L(0); PG8_BAR; PG8_MMA(0, 0, At, B0); PG8_MMA(0, 1, At, B1); PG8_BAR; PG8_SCHED;
;             PG8_LDA(At, 0, 1); PG8_STAGE(PG8_SB(0, 0), b2, voffB); PG8_STAGE(PG8_SB(0, 1), b2 + hstep, voffB); PG8_STAGE(PG8_SA(0, 0), a2, voffA);
;             PG8_WAIT_V(8); PG8_WAIT_L(0); PG8_BAR; PG8_MMA(1, 0, At, B0); PG8_MMA(1, 1, At, B1); PG8_BAR; PG8_SCHED;
;     ...
;         for (int a = 0; a < 2; ++a)
; #pragma unroll
;             for (int b = 0; b < 2; ++b)
; #pragma unroll
;                 for (int m = 0; m < 4; ++m)
; #pragma unroll
;                     for (int n = 0; n < 2; ++n) acc[a][b][m][n] = (f32x4){0.f, 0.f, 0.f, 0.f};
.LBB0_1250:
	s_ashr_i32 s17, s16, 31
	s_lshl_b64 s[18:19], s[16:17], 21
	s_add_u32 s18, s34, s18
	s_addc_u32 s19, s35, s19
	s_ashr_i32 s15, s14, 31
	s_lshl_b64 s[20:21], s[14:15], 21
	s_add_u32 s20, s30, s20
	s_addc_u32 s21, s31, s21
	s_and_b64 s[42:43], s[4:5], exec
	s_cselect_b32 s15, s19, s37
	s_cselect_b32 s17, s18, s36
	s_cselect_b32 s54, s21, s41
	s_cselect_b32 s55, s20, s40
	s_add_u32 s36, s36, 0x100080
	s_addc_u32 s37, s37, 0
	s_add_u32 s56, s40, 0x100
	s_addc_u32 s57, s41, 0
	s_mov_b32 s58, -2
	s_cmp_lt_u32 s24, 0x1000
	s_cbranch_scc0 .Lf1_h1first
	ds_read_b128 v[130:133], v177
	ds_read_b128 v[134:137], v177 offset:1024
	ds_read_b128 v[138:141], v177 offset:2048
	ds_read_b128 v[142:145], v177 offset:3072
	ds_read_b128 v[162:165], v178
	ds_read_b128 v[180:183], v178 offset:1024
	ds_read_b128 v[184:187], v178 offset:2048
	ds_read_b128 v[188:191], v178 offset:3072
	s_add_u32 s40, s36, 0xfff00080
	s_addc_u32 s41, s37, -1
	s_cmp_eq_u32 s58, 60
	s_cselect_b32 s43, s15, s41
	s_cselect_b32 s42, s17, s40
	s_cselect_b32 s41, s54, s57
	s_cselect_b32 s40, s55, s56
	ds_read_b128 v[196:199], v179
	ds_read_b128 v[200:203], v179 offset:1024
	ds_read_b128 v[204:207], v179 offset:2048
	ds_read_b128 v[208:211], v179 offset:3072
	ds_read_b128 v[212:215], v179 offset:4096
	ds_read_b128 v[220:223], v179 offset:5120
	ds_read_b128 v[224:227], v179 offset:6144
	ds_read_b128 v[228:231], v179 offset:7168
	s_add_i32 m0, s24, 0xc000
	s_nop 0
	global_load_lds_dwordx4 v146, s[36:37]
	s_add_i32 m0, s24, 0xe000
	s_nop 0
	global_load_lds_dwordx4 v150, s[36:37]
	s_waitcnt lgkmcnt(0)
	s_setprio 1
	v_mfma_f32_16x16x32_bf16 v[126:129], v[130:133], v[196:199], 0
	v_mfma_f32_16x16x32_bf16 v[126:129], v[134:137], v[200:203], v[126:129]
	v_mfma_f32_16x16x32_bf16 v[122:125], v[138:141], v[196:199], 0
	v_mfma_f32_16x16x32_bf16 v[122:125], v[142:145], v[200:203], v[122:125]
	v_mfma_f32_16x16x32_bf16 v[118:121], v[162:165], v[196:199], 0
	v_mfma_f32_16x16x32_bf16 v[118:121], v[180:183], v[200:203], v[118:121]
	v_mfma_f32_16x16x32_bf16 v[114:117], v[184:187], v[196:199], 0
	v_mfma_f32_16x16x32_bf16 v[114:117], v[188:191], v[200:203], v[114:117]
	v_mfma_f32_16x16x32_bf16 v[98:101], v[184:187], v[204:207], 0
	v_mfma_f32_16x16x32_bf16 v[98:101], v[188:191], v[208:211], v[98:101]
	v_mfma_f32_16x16x32_bf16 v[102:105], v[162:165], v[204:207], 0
	v_mfma_f32_16x16x32_bf16 v[102:105], v[180:183], v[208:211], v[102:105]
	v_mfma_f32_16x16x32_bf16 v[106:109], v[138:141], v[204:207], 0
	v_mfma_f32_16x16x32_bf16 v[106:109], v[142:145], v[208:211], v[106:109]
	v_mfma_f32_16x16x32_bf16 v[110:113], v[130:133], v[204:207], 0
	v_mfma_f32_16x16x32_bf16 v[110:113], v[134:137], v[208:211], v[110:113]
	v_mfma_f32_16x16x32_bf16 v[94:97], v[130:133], v[212:215], 0
	v_mfma_f32_16x16x32_bf16 v[94:97], v[134:137], v[220:223], v[94:97]
	v_mfma_f32_16x16x32_bf16 v[90:93], v[138:141], v[212:215], 0
	v_mfma_f32_16x16x32_bf16 v[90:93], v[142:145], v[220:223], v[90:93]
	v_mfma_f32_16x16x32_bf16 v[86:89], v[162:165], v[212:215], 0
	v_mfma_f32_16x16x32_bf16 v[86:89], v[180:183], v[220:223], v[86:89]
	v_mfma_f32_16x16x32_bf16 v[82:85], v[184:187], v[212:215], 0
	v_mfma_f32_16x16x32_bf16 v[82:85], v[188:191], v[220:223], v[82:85]
	v_mfma_f32_16x16x32_bf16 v[66:69], v[184:187], v[224:227], 0
	v_mfma_f32_16x16x32_bf16 v[66:69], v[188:191], v[228:231], v[66:69]
	v_mfma_f32_16x16x32_bf16 v[70:73], v[162:165], v[224:227], 0
	v_mfma_f32_16x16x32_bf16 v[70:73], v[180:183], v[228:231], v[70:73]
	v_mfma_f32_16x16x32_bf16 v[74:77], v[138:141], v[224:227], 0
	v_mfma_f32_16x16x32_bf16 v[74:77], v[142:145], v[228:231], v[74:77]
	v_mfma_f32_16x16x32_bf16 v[78:81], v[130:133], v[224:227], 0
	v_mfma_f32_16x16x32_bf16 v[78:81], v[134:137], v[228:231], v[78:81]
	s_setprio 0
	s_waitcnt vmcnt(8)
	s_barrier
	ds_read_b128 v[196:199], v179 offset:16384
	ds_read_b128 v[200:203], v179 offset:17408
	ds_read_b128 v[204:207], v179 offset:18432
	ds_read_b128 v[208:211], v179 offset:19456
	ds_read_b128 v[212:215], v179 offset:20480
	ds_read_b128 v[220:223], v179 offset:21504
	ds_read_b128 v[224:227], v179 offset:22528
	ds_read_b128 v[228:231], v179 offset:23552
	s_add_u32 vcc_lo, s40, 0x100000
	s_addc_u32 vcc_hi, s41, 0
	s_add_i32 m0, s24, 0x10000
	s_nop 0
	global_load_lds_dwordx4 v148, s[40:41]
	s_add_i32 m0, s24, 0x12000
	s_nop 0
	global_load_lds_dwordx4 v152, s[40:41]
	s_add_i32 m0, s24, 0x14000
	s_nop 0
	global_load_lds_dwordx4 v148, vcc
	s_add_i32 m0, s24, 0x16000
	s_nop 0
	global_load_lds_dwordx4 v152, vcc
	s_mov_b32 m0, s24
	s_nop 0
	global_load_lds_dwordx4 v146, s[42:43]
	s_add_i32 m0, s24, 0x2000
	s_nop 0
	global_load_lds_dwordx4 v150, s[42:43]
	s_waitcnt lgkmcnt(0)
	s_setprio 1
	v_mfma_f32_16x16x32_bf16 v[62:65], v[130:133], v[196:199], 0
	v_mfma_f32_16x16x32_bf16 v[62:65], v[134:137], v[200:203], v[62:65]
	v_mfma_f32_16x16x32_bf16 v[58:61], v[138:141], v[196:199], 0
	v_mfma_f32_16x16x32_bf16 v[58:61], v[142:145], v[200:203], v[58:61]
	v_mfma_f32_16x16x32_bf16 v[54:57], v[162:165], v[196:199], 0
	v_mfma_f32_16x16x32_bf16 v[54:57], v[180:183], v[200:203], v[54:57]
	v_mfma_f32_16x16x32_bf16 v[50:53], v[184:187], v[196:199], 0
	v_mfma_f32_16x16x32_bf16 v[50:53], v[188:191], v[200:203], v[50:53]
	v_mfma_f32_16x16x32_bf16 v[34:37], v[184:187], v[204:207], 0
	v_mfma_f32_16x16x32_bf16 v[34:37], v[188:191], v[208:211], v[34:37]
	v_mfma_f32_16x16x32_bf16 v[38:41], v[162:165], v[204:207], 0
	v_mfma_f32_16x16x32_bf16 v[38:41], v[180:183], v[208:211], v[38:41]
	v_mfma_f32_16x16x32_bf16 v[42:45], v[138:141], v[204:207], 0
	v_mfma_f32_16x16x32_bf16 v[42:45], v[142:145], v[208:211], v[42:45]
	v_mfma_f32_16x16x32_bf16 v[46:49], v[130:133], v[204:207], 0
	v_mfma_f32_16x16x32_bf16 v[46:49], v[134:137], v[208:211], v[46:49]
	v_mfma_f32_16x16x32_bf16 v[30:33], v[130:133], v[212:215], 0
	v_mfma_f32_16x16x32_bf16 v[30:33], v[134:137], v[220:223], v[30:33]
	v_mfma_f32_16x16x32_bf16 v[26:29], v[138:141], v[212:215], 0
	v_mfma_f32_16x16x32_bf16 v[26:29], v[142:145], v[220:223], v[26:29]
	v_mfma_f32_16x16x32_bf16 v[22:25], v[162:165], v[212:215], 0
	v_mfma_f32_16x16x32_bf16 v[22:25], v[180:183], v[220:223], v[22:25]
	v_mfma_f32_16x16x32_bf16 v[18:21], v[184:187], v[212:215], 0
	v_mfma_f32_16x16x32_bf16 v[18:21], v[188:191], v[220:223], v[18:21]
	v_mfma_f32_16x16x32_bf16 v[2:5], v[184:187], v[224:227], 0
	v_mfma_f32_16x16x32_bf16 v[2:5], v[188:191], v[228:231], v[2:5]
	v_mfma_f32_16x16x32_bf16 v[6:9], v[162:165], v[224:227], 0
	v_mfma_f32_16x16x32_bf16 v[6:9], v[180:183], v[228:231], v[6:9]
	v_mfma_f32_16x16x32_bf16 v[10:13], v[138:141], v[224:227], 0
	v_mfma_f32_16x16x32_bf16 v[10:13], v[142:145], v[228:231], v[10:13]
	v_mfma_f32_16x16x32_bf16 v[14:17], v[130:133], v[224:227], 0
	v_mfma_f32_16x16x32_bf16 v[14:17], v[134:137], v[228:231], v[14:17]
	s_setprio 0
	s_waitcnt vmcnt(8)
	s_barrier
; #define PG8_STAGE(bufoff, gbase, voff) do { _Pragma("unroll") for (int _i = 0; _i < 2; ++_i) \
;         __builtin_amdgcn_global_load_lds((const unsigned*)((const char*)(gbase) + (voff)[_i]), (PG8_LAS unsigned*)(lds + (bufoff) + ldsw + _i * 8192), 16, 0, 0); } while (0)
; #define PG8_LDA(dst, b, h) do { _Pragma("unroll") for (int m = 0; m < 4; ++m) _Pragma("unroll") for (int k = 0; k < 2; ++k) dst[m][k] = *(const PG8_LAS bf16x8*)(lds + PG8_SA(b, h) + aoff + m * 2048 + k * 1024); } while (0)
; #define PG8_LDB(dst, b, h) do { _Pragma("unroll") for (int n = 0; n < 2; ++n) _Pragma("unroll") for (int k = 0; k < 2; ++k) dst[n][k] = *(const PG8_LAS bf16x8*)(lds + PG8_SB(b, h) + boff + n * 2048 + k * 1024); } while (0)
; #define PG8_MMA(ai, bj, At, Bt) do { __builtin_amdgcn_s_setprio(1); _Pragma("unroll") for (int m = 0; m < 4; ++m) _Pragma("unroll") for (int n = 0; n < 2; ++n) _Pragma("unroll") for (int k = 0; k < 2; ++k) \
;         acc[ai][bj][m][n] = __builtin_amdgcn_mfma_f32_16x16x32_bf16(Bt[n][k], At[m][k], acc[ai][bj][m][n], 0, 0, 0); __builtin_amdgcn_s_setprio(0); } while (0)
; #define PG8_WAIT_V(n) asm volatile("s_waitcnt vmcnt(" #n ")" ::: "memory")
; #define PG8_WAIT_L(n) asm volatile("s_waitcnt lgkmcnt(" #n ")" ::: "memory")
; #define PG8_BAR __builtin_amdgcn_s_barrier()
; template <class Epi, class Sched, bool ALIGN_EPI = false, bool SP2 = false>
; __device__ __forceinline__ void gemm_phase(PG8_LAS unsigned char* lds, const Gemm g, const Sched& S, const Epi& E) {
;     ...
;         for (int t = 0; t < nt; t += 2) {
;             const bool last = (t == nt - 2);
;             const char* a1 = cA + (size_t)(t + 1) * kstep;
;             const char* a2 = last ? nA : cA + (size_t)(t + 2) * kstep; const char* b2 = last ? nB : cB + (size_t)(t + 2) * kstep;
;             const char* a3 = a2 + kstep; const char* b3 = b2 + kstep;
;     ...
;             PG8_LDB(B0, 1, 0); PG8_LDB(B1, 1, 1); PG8_SCHED; PG8_LDA(At, 1, 0); PG8_STAGE(PG8_SA(0, 1), a2 + hstep, voffA);
;             PG8_WAIT_V(8); PG8_WAIT_L(0); PG8_BAR; PG8_MMA(0, 0, At, B0); PG8_MMA(0, 1, At, B1); PG8_BAR; PG8_SCHED;
;             PG8_LDA(At, 1, 1); PG8_STAGE(PG8_SB(1, 0), b3, voffB); PG8_STAGE(PG8_SB(1, 1), b3 + hstep, voffB); PG8_STAGE(PG8_SA(1, 0), a3, voffA);
;             PG8_WAIT_V(8); PG8_WAIT_L(0); PG8_BAR; PG8_MMA(1, 0, At, B0); PG8_MMA(1, 1, At, B1); PG8_BAR; PG8_SCHED;
	s_add_i32 s59, 0, 0x18000
	s_add_i32 s60, 0, 0x1c000
	v_add_u32_e32 v142, s59, v166
	v_add_u32_e32 v188, s60, v166
	ds_read_b128 v[130:133], v142
	ds_read_b128 v[134:137], v142 offset:1024
	ds_read_b128 v[138:141], v142 offset:2048
	ds_read_b128 v[142:145], v142 offset:3072
	ds_read_b128 v[162:165], v188
	ds_read_b128 v[180:183], v188 offset:1024
	ds_read_b128 v[184:187], v188 offset:2048
	ds_read_b128 v[188:191], v188 offset:3072
	ds_read_b128 v[196:199], v179 offset:32768
	ds_read_b128 v[200:203], v179 offset:33792
	ds_read_b128 v[204:207], v179 offset:34816
	ds_read_b128 v[208:211], v179 offset:35840
	ds_read_b128 v[212:215], v179 offset:36864
	ds_read_b128 v[220:223], v179 offset:37888
	ds_read_b128 v[224:227], v179 offset:38912
	ds_read_b128 v[228:231], v179 offset:39936
	s_add_u32 vcc_lo, s42, 0x100000
	s_addc_u32 vcc_hi, s43, 0
	s_add_i32 m0, s24, 0x4000
	s_nop 0
	global_load_lds_dwordx4 v146, vcc
	s_add_i32 m0, s24, 0x6000
	s_nop 0
	global_load_lds_dwordx4 v150, vcc
	s_waitcnt lgkmcnt(0)
	s_setprio 1
	v_mfma_f32_16x16x32_bf16 v[126:129], v[130:133], v[196:199], v[126:129]
	v_mfma_f32_16x16x32_bf16 v[126:129], v[134:137], v[200:203], v[126:129]
	v_mfma_f32_16x16x32_bf16 v[122:125], v[138:141], v[196:199], v[122:125]
	v_mfma_f32_16x16x32_bf16 v[122:125], v[142:145], v[200:203], v[122:125]
	v_mfma_f32_16x16x32_bf16 v[118:121], v[162:165], v[196:199], v[118:121]
	v_mfma_f32_16x16x32_bf16 v[118:121], v[180:183], v[200:203], v[118:121]
	v_mfma_f32_16x16x32_bf16 v[114:117], v[184:187], v[196:199], v[114:117]
	v_mfma_f32_16x16x32_bf16 v[114:117], v[188:191], v[200:203], v[114:117]
	v_mfma_f32_16x16x32_bf16 v[98:101], v[184:187], v[204:207], v[98:101]
	v_mfma_f32_16x16x32_bf16 v[98:101], v[188:191], v[208:211], v[98:101]
	v_mfma_f32_16x16x32_bf16 v[102:105], v[162:165], v[204:207], v[102:105]
	v_mfma_f32_16x16x32_bf16 v[102:105], v[180:183], v[208:211], v[102:105]
	v_mfma_f32_16x16x32_bf16 v[106:109], v[138:141], v[204:207], v[106:109]
	v_mfma_f32_16x16x32_bf16 v[106:109], v[142:145], v[208:211], v[106:109]
	v_mfma_f32_16x16x32_bf16 v[110:113], v[130:133], v[204:207], v[110:113]
	v_mfma_f32_16x16x32_bf16 v[110:113], v[134:137], v[208:211], v[110:113]
	v_mfma_f32_16x16x32_bf16 v[94:97], v[130:133], v[212:215], v[94:97]
	v_mfma_f32_16x16x32_bf16 v[94:97], v[134:137], v[220:223], v[94:97]
	v_mfma_f32_16x16x32_bf16 v[90:93], v[138:141], v[212:215], v[90:93]
	v_mfma_f32_16x16x32_bf16 v[90:93], v[142:145], v[220:223], v[90:93]
	v_mfma_f32_16x16x32_bf16 v[86:89], v[162:165], v[212:215], v[86:89]
	v_mfma_f32_16x16x32_bf16 v[86:89], v[180:183], v[220:223], v[86:89]
	v_mfma_f32_16x16x32_bf16 v[82:85], v[184:187], v[212:215], v[82:85]
	v_mfma_f32_16x16x32_bf16 v[82:85], v[188:191], v[220:223], v[82:85]
	v_mfma_f32_16x16x32_bf16 v[66:69], v[184:187], v[224:227], v[66:69]
	v_mfma_f32_16x16x32_bf16 v[66:69], v[188:191], v[228:231], v[66:69]
	v_mfma_f32_16x16x32_bf16 v[70:73], v[162:165], v[224:227], v[70:73]
	v_mfma_f32_16x16x32_bf16 v[70:73], v[180:183], v[228:231], v[70:73]
	v_mfma_f32_16x16x32_bf16 v[74:77], v[138:141], v[224:227], v[74:77]
	v_mfma_f32_16x16x32_bf16 v[74:77], v[142:145], v[228:231], v[74:77]
	v_mfma_f32_16x16x32_bf16 v[78:81], v[130:133], v[224:227], v[78:81]
	v_mfma_f32_16x16x32_bf16 v[78:81], v[134:137], v[228:231], v[78:81]
	s_setprio 0
	s_waitcnt vmcnt(8)
	s_barrier
	ds_read_b128 v[196:199], v179 offset:49152
	ds_read_b128 v[200:203], v179 offset:50176
	ds_read_b128 v[204:207], v179 offset:51200
	ds_read_b128 v[208:211], v179 offset:52224
	ds_read_b128 v[212:215], v179 offset:53248
	ds_read_b128 v[220:223], v179 offset:54272
	ds_read_b128 v[224:227], v179 offset:55296
	ds_read_b128 v[228:231], v179 offset:56320
	s_add_u32 s60, s40, 0x80
	s_addc_u32 s61, s41, 0
	s_add_u32 vcc_lo, s60, 0x100000
	s_addc_u32 vcc_hi, s61, 0
	s_add_i32 m0, s24, 0x18000
	s_nop 0
	global_load_lds_dwordx4 v148, s[60:61]
	s_add_i32 m0, s24, 0x1a000
	s_nop 0
	global_load_lds_dwordx4 v152, s[60:61]
	s_add_i32 m0, s24, 0x1c000
	s_nop 0
	global_load_lds_dwordx4 v148, vcc
	s_add_i32 m0, s24, 0x1e000
	s_nop 0
	global_load_lds_dwordx4 v152, vcc
	s_add_u32 s60, s42, 0x80
	s_addc_u32 s61, s43, 0
	s_add_i32 m0, s24, 0x8000
	s_nop 0
	global_load_lds_dwordx4 v146, s[60:61]
	s_add_i32 m0, s24, 0xa000
	s_nop 0
	global_load_lds_dwordx4 v150, s[60:61]
	s_waitcnt lgkmcnt(0)
	s_setprio 1
	v_mfma_f32_16x16x32_bf16 v[62:65], v[130:133], v[196:199], v[62:65]
	v_mfma_f32_16x16x32_bf16 v[62:65], v[134:137], v[200:203], v[62:65]
	v_mfma_f32_16x16x32_bf16 v[58:61], v[138:141], v[196:199], v[58:61]
	v_mfma_f32_16x16x32_bf16 v[58:61], v[142:145], v[200:203], v[58:61]
	v_mfma_f32_16x16x32_bf16 v[54:57], v[162:165], v[196:199], v[54:57]
	v_mfma_f32_16x16x32_bf16 v[54:57], v[180:183], v[200:203], v[54:57]
	v_mfma_f32_16x16x32_bf16 v[50:53], v[184:187], v[196:199], v[50:53]
	v_mfma_f32_16x16x32_bf16 v[50:53], v[188:191], v[200:203], v[50:53]
	v_mfma_f32_16x16x32_bf16 v[34:37], v[184:187], v[204:207], v[34:37]
	v_mfma_f32_16x16x32_bf16 v[34:37], v[188:191], v[208:211], v[34:37]
	v_mfma_f32_16x16x32_bf16 v[38:41], v[162:165], v[204:207], v[38:41]
	v_mfma_f32_16x16x32_bf16 v[38:41], v[180:183], v[208:211], v[38:41]
	v_mfma_f32_16x16x32_bf16 v[42:45], v[138:141], v[204:207], v[42:45]
	v_mfma_f32_16x16x32_bf16 v[42:45], v[142:145], v[208:211], v[42:45]
	v_mfma_f32_16x16x32_bf16 v[46:49], v[130:133], v[204:207], v[46:49]
	v_mfma_f32_16x16x32_bf16 v[46:49], v[134:137], v[208:211], v[46:49]
	v_mfma_f32_16x16x32_bf16 v[30:33], v[130:133], v[212:215], v[30:33]
	v_mfma_f32_16x16x32_bf16 v[30:33], v[134:137], v[220:223], v[30:33]
	v_mfma_f32_16x16x32_bf16 v[26:29], v[138:141], v[212:215], v[26:29]
	v_mfma_f32_16x16x32_bf16 v[26:29], v[142:145], v[220:223], v[26:29]
	v_mfma_f32_16x16x32_bf16 v[22:25], v[162:165], v[212:215], v[22:25]
	v_mfma_f32_16x16x32_bf16 v[22:25], v[180:183], v[220:223], v[22:25]
	v_mfma_f32_16x16x32_bf16 v[18:21], v[184:187], v[212:215], v[18:21]
	v_mfma_f32_16x16x32_bf16 v[18:21], v[188:191], v[220:223], v[18:21]
	v_mfma_f32_16x16x32_bf16 v[2:5], v[184:187], v[224:227], v[2:5]
	v_mfma_f32_16x16x32_bf16 v[2:5], v[188:191], v[228:231], v[2:5]
	v_mfma_f32_16x16x32_bf16 v[6:9], v[162:165], v[224:227], v[6:9]
	v_mfma_f32_16x16x32_bf16 v[6:9], v[180:183], v[228:231], v[6:9]
	v_mfma_f32_16x16x32_bf16 v[10:13], v[138:141], v[224:227], v[10:13]
	v_mfma_f32_16x16x32_bf16 v[10:13], v[142:145], v[228:231], v[10:13]
	v_mfma_f32_16x16x32_bf16 v[14:17], v[130:133], v[224:227], v[14:17]
	v_mfma_f32_16x16x32_bf16 v[14:17], v[134:137], v[228:231], v[14:17]
	s_setprio 0
	s_waitcnt vmcnt(8)
	s_barrier
	s_add_i32 s58, s58, 2
	s_add_u32 s36, s36, 0x100
	s_addc_u32 s37, s37, 0
	s_add_u32 s56, s56, 0x100
	s_addc_u32 s57, s57, 0
	s_cmp_gt_u32 s58, 61

; #define PG8_STAGE(bufoff, gbase, voff) do { _Pragma("unroll") for (int _i = 0; _i < 2; ++_i) \
;         __builtin_amdgcn_global_load_lds((const unsigned*)((const char*)(gbase) + (voff)[_i]), (PG8_LAS unsigned*)(lds + (bufoff) + ldsw + _i * 8192), 16, 0, 0); } while (0)
; #define PG8_LDA(dst, b, h) do { _Pragma("unroll") for (int m = 0; m < 4; ++m) _Pragma("unroll") for (int k = 0; k < 2; ++k) dst[m][k] = *(const PG8_LAS bf16x8*)(lds + PG8_SA(b, h) + aoff + m * 2048 + k * 1024); } while (0)
; #define PG8_LDB(dst, b, h) do { _Pragma("unroll") for (int n = 0; n < 2; ++n) _Pragma("unroll") for (int k = 0; k < 2; ++k) dst[n][k] = *(const PG8_LAS bf16x8*)(lds + PG8_SB(b, h) + boff + n * 2048 + k * 1024); } while (0)
; #define PG8_MMA(ai, bj, At, Bt) do { __builtin_amdgcn_s_setprio(1); _Pragma("unroll") for (int m = 0; m < 4; ++m) _Pragma("unroll") for (int n = 0; n < 2; ++n) _Pragma("unroll") for (int k = 0; k < 2; ++k) \
;         acc[ai][bj][m][n] = __builtin_amdgcn_mfma_f32_16x16x32_bf16(Bt[n][k], At[m][k], acc[ai][bj][m][n], 0, 0, 0); __builtin_amdgcn_s_setprio(0); } while (0)
; #define PG8_WAIT_V(n) asm volatile("s_waitcnt vmcnt(" #n ")" ::: "memory")
; #define PG8_WAIT_L(n) asm volatile("s_waitcnt lgkmcnt(" #n ")" ::: "memory")
; #define PG8_BAR __builtin_amdgcn_s_barrier()
; #define PG8_SCHED __builtin_amdgcn_sched_barrier(0)
; template <class Epi, class Sched, bool ALIGN_EPI = false, bool SP2 = false>
; __device__ __forceinline__ void gemm_phase(PG8_LAS unsigned char* lds, const Gemm g, const Sched& S, const Epi& E) {
;     ...
;             PG8_LDB(B0, 0, 0); PG8_LDB(B1, 0, 1); PG8_SCHED; PG8_LDA(At, 0, 0); PG8_STAGE(PG8_SA(1, 1), a1 + hstep, voffA);
;             PG8_WAIT_V(8); PG8_WAIT_L(0); PG8_BAR; PG8_MMA(0, 0, At, B0); PG8_MMA(0, 1, At, B1); PG8_BAR; PG8_SCHED;
;             PG8_LDA(At, 0, 1); PG8_STAGE(PG8_SB(0, 0), b2, voffB); PG8_STAGE(PG8_SB(0, 1), b2 + hstep, voffB); PG8_STAGE(PG8_SA(0, 0), a2, voffA);
;             PG8_WAIT_V(8); PG8_WAIT_L(0); PG8_BAR; PG8_MMA(1, 0, At, B0); PG8_MMA(1, 1, At, B1); PG8_BAR; PG8_SCHED;
.Lf1_h1first:
	ds_read_b128 v[130:133], v177
	ds_read_b128 v[134:137], v177 offset:1024
	ds_read_b128 v[138:141], v177 offset:2048
	ds_read_b128 v[142:145], v177 offset:3072
	ds_read_b128 v[162:165], v178
	ds_read_b128 v[180:183], v178 offset:1024
	ds_read_b128 v[184:187], v178 offset:2048
	ds_read_b128 v[188:191], v178 offset:3072
	s_add_u32 s40, s36, 0xfff00080
	s_addc_u32 s41, s37, -1
	s_cmp_eq_u32 s58, 60
	s_cselect_b32 s43, s15, s41
	s_cselect_b32 s42, s17, s40
	s_cselect_b32 s41, s54, s57
	s_cselect_b32 s40, s55, s56
	ds_read_b128 v[196:199], v179
	ds_read_b128 v[200:203], v179 offset:1024
	ds_read_b128 v[204:207], v179 offset:2048
	ds_read_b128 v[208:211], v179 offset:3072
	ds_read_b128 v[212:215], v179 offset:4096
	ds_read_b128 v[220:223], v179 offset:5120
	ds_read_b128 v[224:227], v179 offset:6144
	ds_read_b128 v[228:231], v179 offset:7168
	s_add_i32 m0, s24, 0xc000
	s_nop 0
	global_load_lds_dwordx4 v146, s[36:37]
	s_add_i32 m0, s24, 0xe000
	s_nop 0
	global_load_lds_dwordx4 v150, s[36:37]
	s_sleep 2
	s_waitcnt lgkmcnt(0)
	s_waitcnt vmcnt(8)
	s_barrier
	s_setprio 2
	v_mfma_f32_16x16x32_bf16 v[126:129], v[130:133], v[196:199], 0
	v_mfma_f32_16x16x32_bf16 v[126:129], v[134:137], v[200:203], v[126:129]
	v_mfma_f32_16x16x32_bf16 v[122:125], v[138:141], v[196:199], 0
	v_mfma_f32_16x16x32_bf16 v[122:125], v[142:145], v[200:203], v[122:125]
	v_mfma_f32_16x16x32_bf16 v[118:121], v[162:165], v[196:199], 0
	v_mfma_f32_16x16x32_bf16 v[118:121], v[180:183], v[200:203], v[118:121]
	v_mfma_f32_16x16x32_bf16 v[114:117], v[184:187], v[196:199], 0
	v_mfma_f32_16x16x32_bf16 v[114:117], v[188:191], v[200:203], v[114:117]
	v_mfma_f32_16x16x32_bf16 v[98:101], v[184:187], v[204:207], 0
	v_mfma_f32_16x16x32_bf16 v[98:101], v[188:191], v[208:211], v[98:101]
	v_mfma_f32_16x16x32_bf16 v[102:105], v[162:165], v[204:207], 0
	v_mfma_f32_16x16x32_bf16 v[102:105], v[180:183], v[208:211], v[102:105]
	v_mfma_f32_16x16x32_bf16 v[106:109], v[138:141], v[204:207], 0
	v_mfma_f32_16x16x32_bf16 v[106:109], v[142:145], v[208:211], v[106:109]
	v_mfma_f32_16x16x32_bf16 v[110:113], v[130:133], v[204:207], 0
	v_mfma_f32_16x16x32_bf16 v[110:113], v[134:137], v[208:211], v[110:113]
	v_mfma_f32_16x16x32_bf16 v[94:97], v[130:133], v[212:215], 0
	v_mfma_f32_16x16x32_bf16 v[94:97], v[134:137], v[220:223], v[94:97]
	v_mfma_f32_16x16x32_bf16 v[90:93], v[138:141], v[212:215], 0
	v_mfma_f32_16x16x32_bf16 v[90:93], v[142:145], v[220:223], v[90:93]
	v_mfma_f32_16x16x32_bf16 v[86:89], v[162:165], v[212:215], 0
	v_mfma_f32_16x16x32_bf16 v[86:89], v[180:183], v[220:223], v[86:89]
	v_mfma_f32_16x16x32_bf16 v[82:85], v[184:187], v[212:215], 0
	v_mfma_f32_16x16x32_bf16 v[82:85], v[188:191], v[220:223], v[82:85]
	v_mfma_f32_16x16x32_bf16 v[66:69], v[184:187], v[224:227], 0
	v_mfma_f32_16x16x32_bf16 v[66:69], v[188:191], v[228:231], v[66:69]
	v_mfma_f32_16x16x32_bf16 v[70:73], v[162:165], v[224:227], 0
	v_mfma_f32_16x16x32_bf16 v[70:73], v[180:183], v[228:231], v[70:73]
	v_mfma_f32_16x16x32_bf16 v[74:77], v[138:141], v[224:227], 0
	v_mfma_f32_16x16x32_bf16 v[74:77], v[142:145], v[228:231], v[74:77]
	v_mfma_f32_16x16x32_bf16 v[78:81], v[130:133], v[224:227], 0
	v_mfma_f32_16x16x32_bf16 v[78:81], v[134:137], v[228:231], v[78:81]
	s_setprio 0
	ds_read_b128 v[196:199], v179 offset:16384
	ds_read_b128 v[200:203], v179 offset:17408
	ds_read_b128 v[204:207], v179 offset:18432
	ds_read_b128 v[208:211], v179 offset:19456
	ds_read_b128 v[212:215], v179 offset:20480
	ds_read_b128 v[220:223], v179 offset:21504
	ds_read_b128 v[224:227], v179 offset:22528
	ds_read_b128 v[228:231], v179 offset:23552
	s_add_u32 vcc_lo, s40, 0x100000
	s_addc_u32 vcc_hi, s41, 0
	s_add_i32 m0, s24, 0x10000
	s_nop 0
	global_load_lds_dwordx4 v148, s[40:41]
	s_add_i32 m0, s24, 0x12000
	s_nop 0
	global_load_lds_dwordx4 v152, s[40:41]
	s_add_i32 m0, s24, 0x14000
	s_nop 0
	global_load_lds_dwordx4 v148, vcc
	s_add_i32 m0, s24, 0x16000
	s_nop 0
	global_load_lds_dwordx4 v152, vcc
	s_mov_b32 m0, s24
	s_nop 0
	global_load_lds_dwordx4 v146, s[42:43]
	s_add_i32 m0, s24, 0x2000
	s_nop 0
	global_load_lds_dwordx4 v150, s[42:43]
	s_sleep 2
	s_waitcnt lgkmcnt(0)
	s_waitcnt vmcnt(8)
	s_barrier
	s_setprio 2
	v_mfma_f32_16x16x32_bf16 v[62:65], v[130:133], v[196:199], 0
	v_mfma_f32_16x16x32_bf16 v[62:65], v[134:137], v[200:203], v[62:65]
	v_mfma_f32_16x16x32_bf16 v[58:61], v[138:141], v[196:199], 0
	v_mfma_f32_16x16x32_bf16 v[58:61], v[142:145], v[200:203], v[58:61]
	v_mfma_f32_16x16x32_bf16 v[54:57], v[162:165], v[196:199], 0
	v_mfma_f32_16x16x32_bf16 v[54:57], v[180:183], v[200:203], v[54:57]
	v_mfma_f32_16x16x32_bf16 v[50:53], v[184:187], v[196:199], 0
	v_mfma_f32_16x16x32_bf16 v[50:53], v[188:191], v[200:203], v[50:53]
	v_mfma_f32_16x16x32_bf16 v[34:37], v[184:187], v[204:207], 0
	v_mfma_f32_16x16x32_bf16 v[34:37], v[188:191], v[208:211], v[34:37]
	v_mfma_f32_16x16x32_bf16 v[38:41], v[162:165], v[204:207], 0
	v_mfma_f32_16x16x32_bf16 v[38:41], v[180:183], v[208:211], v[38:41]
	v_mfma_f32_16x16x32_bf16 v[42:45], v[138:141], v[204:207], 0
	v_mfma_f32_16x16x32_bf16 v[42:45], v[142:145], v[208:211], v[42:45]
	v_mfma_f32_16x16x32_bf16 v[46:49], v[130:133], v[204:207], 0
	v_mfma_f32_16x16x32_bf16 v[46:49], v[134:137], v[208:211], v[46:49]
	v_mfma_f32_16x16x32_bf16 v[30:33], v[130:133], v[212:215], 0
	v_mfma_f32_16x16x32_bf16 v[30:33], v[134:137], v[220:223], v[30:33]
	v_mfma_f32_16x16x32_bf16 v[26:29], v[138:141], v[212:215], 0
	v_mfma_f32_16x16x32_bf16 v[26:29], v[142:145], v[220:223], v[26:29]
	v_mfma_f32_16x16x32_bf16 v[22:25], v[162:165], v[212:215], 0
	v_mfma_f32_16x16x32_bf16 v[22:25], v[180:183], v[220:223], v[22:25]
; #define PG8_STAGE(bufoff, gbase, voff) do { _Pragma("unroll") for (int _i = 0; _i < 2; ++_i) \
;         __builtin_amdgcn_global_load_lds((const unsigned*)((const char*)(gbase) + (voff)[_i]), (PG8_LAS unsigned*)(lds + (bufoff) + ldsw + _i * 8192), 16, 0, 0); } while (0)
; #define PG8_LDA(dst, b, h) do { _Pragma("unroll") for (int m = 0; m < 4; ++m) _Pragma("unroll") for (int k = 0; k < 2; ++k) dst[m][k] = *(const PG8_LAS bf16x8*)(lds + PG8_SA(b, h) + aoff + m * 2048 + k * 1024); } while (0)
; #define PG8_LDB(dst, b, h) do { _Pragma("unroll") for (int n = 0; n < 2; ++n) _Pragma("unroll") for (int k = 0; k < 2; ++k) dst[n][k] = *(const PG8_LAS bf16x8*)(lds + PG8_SB(b, h) + boff + n * 2048 + k * 1024); } while (0)
; #define PG8_MMA(ai, bj, At, Bt) do { __builtin_amdgcn_s_setprio(1); _Pragma("unroll") for (int m = 0; m < 4; ++m) _Pragma("unroll") for (int n = 0; n < 2; ++n) _Pragma("unroll") for (int k = 0; k < 2; ++k) \
;         acc[ai][bj][m][n] = __builtin_amdgcn_mfma_f32_16x16x32_bf16(Bt[n][k], At[m][k], acc[ai][bj][m][n], 0, 0, 0); __builtin_amdgcn_s_setprio(0); } while (0)
; #define PG8_WAIT_V(n) asm volatile("s_waitcnt vmcnt(" #n ")" ::: "memory")
; #define PG8_WAIT_L(n) asm volatile("s_waitcnt lgkmcnt(" #n ")" ::: "memory")
; #define PG8_BAR __builtin_amdgcn_s_barrier()
; #define PG8_SCHED __builtin_amdgcn_sched_barrier(0)
; template <class Epi, class Sched, bool ALIGN_EPI = false, bool SP2 = false>
; __device__ __forceinline__ void gemm_phase(PG8_LAS unsigned char* lds, const Gemm g, const Sched& S, const Epi& E) {
;     ...
;             PG8_WAIT_V(8); PG8_WAIT_L(0); PG8_BAR; PG8_MMA(1, 0, At, B0); PG8_MMA(1, 1, At, B1); PG8_BAR; PG8_SCHED;
;             PG8_LDB(B0, 1, 0); PG8_LDB(B1, 1, 1); PG8_SCHED; PG8_LDA(At, 1, 0); PG8_STAGE(PG8_SA(0, 1), a2 + hstep, voffA);
;             PG8_WAIT_V(8); PG8_WAIT_L(0); PG8_BAR; PG8_MMA(0, 0, At, B0); PG8_MMA(0, 1, At, B1); PG8_BAR; PG8_SCHED;
;             PG8_LDA(At, 1, 1); PG8_STAGE(PG8_SB(1, 0), b3, voffB); PG8_STAGE(PG8_SB(1, 1), b3 + hstep, voffB); PG8_STAGE(PG8_SA(1, 0), a3, voffA);
	v_mfma_f32_16x16x32_bf16 v[18:21], v[184:187], v[212:215], 0
	v_mfma_f32_16x16x32_bf16 v[18:21], v[188:191], v[220:223], v[18:21]
	v_mfma_f32_16x16x32_bf16 v[2:5], v[184:187], v[224:227], 0
	v_mfma_f32_16x16x32_bf16 v[2:5], v[188:191], v[228:231], v[2:5]
	v_mfma_f32_16x16x32_bf16 v[6:9], v[162:165], v[224:227], 0
	v_mfma_f32_16x16x32_bf16 v[6:9], v[180:183], v[228:231], v[6:9]
	v_mfma_f32_16x16x32_bf16 v[10:13], v[138:141], v[224:227], 0
	v_mfma_f32_16x16x32_bf16 v[10:13], v[142:145], v[228:231], v[10:13]
	v_mfma_f32_16x16x32_bf16 v[14:17], v[130:133], v[224:227], 0
	v_mfma_f32_16x16x32_bf16 v[14:17], v[134:137], v[228:231], v[14:17]
	s_setprio 0
	s_add_i32 s59, 0, 0x18000
	s_add_i32 s60, 0, 0x1c000
	v_add_u32_e32 v142, s59, v166
	v_add_u32_e32 v188, s60, v166
	ds_read_b128 v[130:133], v142
	ds_read_b128 v[134:137], v142 offset:1024
	ds_read_b128 v[138:141], v142 offset:2048
	ds_read_b128 v[142:145], v142 offset:3072
	ds_read_b128 v[162:165], v188
	ds_read_b128 v[180:183], v188 offset:1024
	ds_read_b128 v[184:187], v188 offset:2048
	ds_read_b128 v[188:191], v188 offset:3072
	ds_read_b128 v[196:199], v179 offset:32768
	ds_read_b128 v[200:203], v179 offset:33792
	ds_read_b128 v[204:207], v179 offset:34816
	ds_read_b128 v[208:211], v179 offset:35840
	ds_read_b128 v[212:215], v179 offset:36864
	ds_read_b128 v[220:223], v179 offset:37888
	ds_read_b128 v[224:227], v179 offset:38912
	ds_read_b128 v[228:231], v179 offset:39936
	s_add_u32 vcc_lo, s42, 0x100000
	s_addc_u32 vcc_hi, s43, 0
	s_add_i32 m0, s24, 0x4000
	s_nop 0
	global_load_lds_dwordx4 v146, vcc
	s_add_i32 m0, s24, 0x6000
	s_nop 0
	global_load_lds_dwordx4 v150, vcc
	s_sleep 2
	s_waitcnt lgkmcnt(0)
	s_waitcnt vmcnt(8)
	s_barrier
	s_setprio 2
	v_mfma_f32_16x16x32_bf16 v[126:129], v[130:133], v[196:199], v[126:129]
	v_mfma_f32_16x16x32_bf16 v[126:129], v[134:137], v[200:203], v[126:129]
	v_mfma_f32_16x16x32_bf16 v[122:125], v[138:141], v[196:199], v[122:125]
	v_mfma_f32_16x16x32_bf16 v[122:125], v[142:145], v[200:203], v[122:125]
	v_mfma_f32_16x16x32_bf16 v[118:121], v[162:165], v[196:199], v[118:121]
	v_mfma_f32_16x16x32_bf16 v[118:121], v[180:183], v[200:203], v[118:121]
	v_mfma_f32_16x16x32_bf16 v[114:117], v[184:187], v[196:199], v[114:117]
	v_mfma_f32_16x16x32_bf16 v[114:117], v[188:191], v[200:203], v[114:117]
	v_mfma_f32_16x16x32_bf16 v[98:101], v[184:187], v[204:207], v[98:101]
	v_mfma_f32_16x16x32_bf16 v[98:101], v[188:191], v[208:211], v[98:101]
	v_mfma_f32_16x16x32_bf16 v[102:105], v[162:165], v[204:207], v[102:105]
	v_mfma_f32_16x16x32_bf16 v[102:105], v[180:183], v[208:211], v[102:105]
	v_mfma_f32_16x16x32_bf16 v[106:109], v[138:141], v[204:207], v[106:109]
	v_mfma_f32_16x16x32_bf16 v[106:109], v[142:145], v[208:211], v[106:109]
	v_mfma_f32_16x16x32_bf16 v[110:113], v[130:133], v[204:207], v[110:113]
	v_mfma_f32_16x16x32_bf16 v[110:113], v[134:137], v[208:211], v[110:113]
	v_mfma_f32_16x16x32_bf16 v[94:97], v[130:133], v[212:215], v[94:97]
	v_mfma_f32_16x16x32_bf16 v[94:97], v[134:137], v[220:223], v[94:97]
	v_mfma_f32_16x16x32_bf16 v[90:93], v[138:141], v[212:215], v[90:93]
	v_mfma_f32_16x16x32_bf16 v[90:93], v[142:145], v[220:223], v[90:93]
	v_mfma_f32_16x16x32_bf16 v[86:89], v[162:165], v[212:215], v[86:89]
	v_mfma_f32_16x16x32_bf16 v[86:89], v[180:183], v[220:223], v[86:89]
	v_mfma_f32_16x16x32_bf16 v[82:85], v[184:187], v[212:215], v[82:85]
	v_mfma_f32_16x16x32_bf16 v[82:85], v[188:191], v[220:223], v[82:85]
	v_mfma_f32_16x16x32_bf16 v[66:69], v[184:187], v[224:227], v[66:69]
	v_mfma_f32_16x16x32_bf16 v[66:69], v[188:191], v[228:231], v[66:69]
	v_mfma_f32_16x16x32_bf16 v[70:73], v[162:165], v[224:227], v[70:73]
	v_mfma_f32_16x16x32_bf16 v[70:73], v[180:183], v[228:231], v[70:73]
	v_mfma_f32_16x16x32_bf16 v[74:77], v[138:141], v[224:227], v[74:77]
	v_mfma_f32_16x16x32_bf16 v[74:77], v[142:145], v[228:231], v[74:77]
	v_mfma_f32_16x16x32_bf16 v[78:81], v[130:133], v[224:227], v[78:81]
	v_mfma_f32_16x16x32_bf16 v[78:81], v[134:137], v[228:231], v[78:81]
	s_setprio 0
	ds_read_b128 v[196:199], v179 offset:49152
	ds_read_b128 v[200:203], v179 offset:50176
	ds_read_b128 v[204:207], v179 offset:51200
	ds_read_b128 v[208:211], v179 offset:52224
	ds_read_b128 v[212:215], v179 offset:53248
	ds_read_b128 v[220:223], v179 offset:54272
	ds_read_b128 v[224:227], v179 offset:55296
	ds_read_b128 v[228:231], v179 offset:56320
	s_add_u32 s60, s40, 0x80
	s_addc_u32 s61, s41, 0
	s_add_u32 vcc_lo, s60, 0x100000
	s_addc_u32 vcc_hi, s61, 0
	s_add_i32 m0, s24, 0x18000
	s_nop 0
	global_load_lds_dwordx4 v148, s[60:61]
	s_add_i32 m0, s24, 0x1a000
	s_nop 0
	global_load_lds_dwordx4 v152, s[60:61]
	s_add_i32 m0, s24, 0x1c000
	s_nop 0
	global_load_lds_dwordx4 v148, vcc
	s_add_i32 m0, s24, 0x1e000
	s_nop 0
	global_load_lds_dwordx4 v152, vcc
	s_add_u32 s60, s42, 0x80
	s_addc_u32 s61, s43, 0
	s_add_i32 m0, s24, 0x8000
	s_nop 0
	global_load_lds_dwordx4 v146, s[60:61]
	s_add_i32 m0, s24, 0xa000
	s_nop 0
	global_load_lds_dwordx4 v150, s[60:61]
	s_sleep 2
	s_waitcnt lgkmcnt(0)
	s_waitcnt vmcnt(8)
	s_barrier
; #define PG8_STAGE(bufoff, gbase, voff) do { _Pragma("unroll") for (int _i = 0; _i < 2; ++_i) \
;         __builtin_amdgcn_global_load_lds((const unsigned*)((const char*)(gbase) + (voff)[_i]), (PG8_LAS unsigned*)(lds + (bufoff) + ldsw + _i * 8192), 16, 0, 0); } while (0)
; #define PG8_LDA(dst, b, h) do { _Pragma("unroll") for (int m = 0; m < 4; ++m) _Pragma("unroll") for (int k = 0; k < 2; ++k) dst[m][k] = *(const PG8_LAS bf16x8*)(lds + PG8_SA(b, h) + aoff + m * 2048 + k * 1024); } while (0)
; #define PG8_LDB(dst, b, h) do { _Pragma("unroll") for (int n = 0; n < 2; ++n) _Pragma("unroll") for (int k = 0; k < 2; ++k) dst[n][k] = *(const PG8_LAS bf16x8*)(lds + PG8_SB(b, h) + boff + n * 2048 + k * 1024); } while (0)
; #define PG8_MMA(ai, bj, At, Bt) do { __builtin_amdgcn_s_setprio(1); _Pragma("unroll") for (int m = 0; m < 4; ++m) _Pragma("unroll") for (int n = 0; n < 2; ++n) _Pragma("unroll") for (int k = 0; k < 2; ++k) \
;         acc[ai][bj][m][n] = __builtin_amdgcn_mfma_f32_16x16x32_bf16(Bt[n][k], At[m][k], acc[ai][bj][m][n], 0, 0, 0); __builtin_amdgcn_s_setprio(0); } while (0)
; #define PG8_WAIT_V(n) asm volatile("s_waitcnt vmcnt(" #n ")" ::: "memory")
; #define PG8_WAIT_L(n) asm volatile("s_waitcnt lgkmcnt(" #n ")" ::: "memory")
; #define PG8_BAR __builtin_amdgcn_s_barrier()
; #define PG8_SCHED __builtin_amdgcn_sched_barrier(0)
; template <class Epi, class Sched, bool ALIGN_EPI = false, bool SP2 = false>
; __device__ __forceinline__ void gemm_phase(PG8_LAS unsigned char* lds, const Gemm g, const Sched& S, const Epi& E) {
;     ...
;         for (int t = 0; t < nt; t += 2) {
;             const bool last = (t == nt - 2);
;     ...
;             PG8_WAIT_V(8); PG8_WAIT_L(0); PG8_BAR; PG8_MMA(1, 0, At, B0); PG8_MMA(1, 1, At, B1); PG8_BAR; PG8_SCHED;
;             PG8_LDB(B0, 1, 0); PG8_LDB(B1, 1, 1); PG8_SCHED; PG8_LDA(At, 1, 0); PG8_STAGE(PG8_SA(0, 1), a2 + hstep, voffA);
;             PG8_WAIT_V(8); PG8_WAIT_L(0); PG8_BAR; PG8_MMA(0, 0, At, B0); PG8_MMA(0, 1, At, B1); PG8_BAR; PG8_SCHED;
;             PG8_LDA(At, 1, 1); PG8_STAGE(PG8_SB(1, 0), b3, voffB); PG8_STAGE(PG8_SB(1, 1), b3 + hstep, voffB); PG8_STAGE(PG8_SA(1, 0), a3, voffA);
;             PG8_WAIT_V(8); PG8_WAIT_L(0); PG8_BAR; PG8_MMA(1, 0, At, B0); PG8_MMA(1, 1, At, B1); PG8_BAR; PG8_SCHED;
	s_setprio 2
	v_mfma_f32_16x16x32_bf16 v[62:65], v[130:133], v[196:199], v[62:65]
	v_mfma_f32_16x16x32_bf16 v[62:65], v[134:137], v[200:203], v[62:65]
	v_mfma_f32_16x16x32_bf16 v[58:61], v[138:141], v[196:199], v[58:61]
	v_mfma_f32_16x16x32_bf16 v[58:61], v[142:145], v[200:203], v[58:61]
	v_mfma_f32_16x16x32_bf16 v[54:57], v[162:165], v[196:199], v[54:57]
	v_mfma_f32_16x16x32_bf16 v[54:57], v[180:183], v[200:203], v[54:57]
	v_mfma_f32_16x16x32_bf16 v[50:53], v[184:187], v[196:199], v[50:53]
	v_mfma_f32_16x16x32_bf16 v[50:53], v[188:191], v[200:203], v[50:53]
	v_mfma_f32_16x16x32_bf16 v[34:37], v[184:187], v[204:207], v[34:37]
	v_mfma_f32_16x16x32_bf16 v[34:37], v[188:191], v[208:211], v[34:37]
	v_mfma_f32_16x16x32_bf16 v[38:41], v[162:165], v[204:207], v[38:41]
	v_mfma_f32_16x16x32_bf16 v[38:41], v[180:183], v[208:211], v[38:41]
	v_mfma_f32_16x16x32_bf16 v[42:45], v[138:141], v[204:207], v[42:45]
	v_mfma_f32_16x16x32_bf16 v[42:45], v[142:145], v[208:211], v[42:45]
	v_mfma_f32_16x16x32_bf16 v[46:49], v[130:133], v[204:207], v[46:49]
	v_mfma_f32_16x16x32_bf16 v[46:49], v[134:137], v[208:211], v[46:49]
	v_mfma_f32_16x16x32_bf16 v[30:33], v[130:133], v[212:215], v[30:33]
	v_mfma_f32_16x16x32_bf16 v[30:33], v[134:137], v[220:223], v[30:33]
	v_mfma_f32_16x16x32_bf16 v[26:29], v[138:141], v[212:215], v[26:29]
	v_mfma_f32_16x16x32_bf16 v[26:29], v[142:145], v[220:223], v[26:29]
	v_mfma_f32_16x16x32_bf16 v[22:25], v[162:165], v[212:215], v[22:25]
	v_mfma_f32_16x16x32_bf16 v[22:25], v[180:183], v[220:223], v[22:25]
	v_mfma_f32_16x16x32_bf16 v[18:21], v[184:187], v[212:215], v[18:21]
	v_mfma_f32_16x16x32_bf16 v[18:21], v[188:191], v[220:223], v[18:21]
	v_mfma_f32_16x16x32_bf16 v[2:5], v[184:187], v[224:227], v[2:5]
	v_mfma_f32_16x16x32_bf16 v[2:5], v[188:191], v[228:231], v[2:5]
	v_mfma_f32_16x16x32_bf16 v[6:9], v[162:165], v[224:227], v[6:9]
	v_mfma_f32_16x16x32_bf16 v[6:9], v[180:183], v[228:231], v[6:9]
	v_mfma_f32_16x16x32_bf16 v[10:13], v[138:141], v[224:227], v[10:13]
	v_mfma_f32_16x16x32_bf16 v[10:13], v[142:145], v[228:231], v[10:13]
	v_mfma_f32_16x16x32_bf16 v[14:17], v[130:133], v[224:227], v[14:17]
	v_mfma_f32_16x16x32_bf16 v[14:17], v[134:137], v[228:231], v[14:17]
	s_setprio 0
	s_add_i32 s58, s58, 2
	s_add_u32 s36, s36, 0x100
	s_addc_u32 s37, s37, 0
	s_add_u32 s56, s56, 0x100
	s_addc_u32 s57, s57, 0
	s_cmp_gt_u32 s58, 61

; template <class Epi, class Sched, bool ALIGN_EPI = false, bool SP2 = false>
; __device__ __forceinline__ void gemm_phase(PG8_LAS unsigned char* lds, const Gemm g, const Sched& S, const Epi& E) {
;     ...
;         const bool has_next = S.next(ui + 1, nxt);
;         const char* nA = cA; const char* nB = cB; if (has_next) S.bases(nxt, g, tstep, nA, nB);
;         for (int t = 0; t < nt; t += 2) {
;             const bool last = (t == nt - 2);
;             const char* a1 = cA + (size_t)(t + 1) * kstep;
;             const char* a2 = last ? nA : cA + (size_t)(t + 2) * kstep; const char* b2 = last ? nB : cB + (size_t)(t + 2) * kstep;
;             const char* a3 = a2 + kstep; const char* b3 = b2 + kstep;
;             if (last && has_next) S.a_ready(nxt);
;             if constexpr (Epi::MIDK) { if (t == (nt >> 1)) { E.midk(acc, wr, fr); asm volatile("s_waitcnt lgkmcnt(0)" ::: "memory"); } }
;             if constexpr (SP2) {
;             PG8_LDB(B0, 0, 0); PG8_LDB(B1, 0, 1); PG8_SCHED; PG8_LDA(At, 0, 0); PG8_STAGE(PG8_SA(1, 1), a1 + hstep, voffA);
;             PG8_WAIT_V(8); PG8_WAIT_L(0); PG8_BAR; PG8_MMA(0, 0, At, B0); PG8_MMA(0, 1, At, B1); PG8_BAR; PG8_SCHED;
;             PG8_LDA(At, 0, 1); PG8_STAGE(PG8_SB(0, 0), b2, voffB); PG8_STAGE(PG8_SB(0, 1), b2 + hstep, voffB); PG8_STAGE(PG8_SA(0, 0), a2, voffA);
;             PG8_WAIT_V(8); PG8_WAIT_L(0); PG8_BAR; PG8_MMA(1, 0, At, B0); PG8_MMA(1, 1, At, B1); PG8_BAR; PG8_SCHED;
;             PG8_LDB(B0, 1, 0); PG8_LDB(B1, 1, 1); PG8_SCHED; PG8_LDA(At, 1, 0); PG8_STAGE(PG8_SA(0, 1), a2 + hstep, voffA);
;             PG8_WAIT_V(8); PG8_WAIT_L(0); PG8_BAR; PG8_MMA(0, 0, At, B0); PG8_MMA(0, 1, At, B1); PG8_BAR; PG8_SCHED;
;             PG8_LDA(At, 1, 1); PG8_STAGE(PG8_SB(1, 0), b3, voffB); PG8_STAGE(PG8_SB(1, 1), b3 + hstep, voffB); PG8_STAGE(PG8_SA(1, 0), a3, voffA);
;             PG8_WAIT_V(8); PG8_WAIT_L(0); PG8_BAR; PG8_MMA(1, 0, At, B0); PG8_MMA(1, 1, At, B1); PG8_BAR; PG8_SCHED;
;             } else {
;             PG8_LDB(B0, 0, 0); PG8_SCHED; PG8_LDA(At, 0, 0); PG8_STAGE(PG8_SA(1, 1), a1 + hstep, voffA);
;     ...
;         for (int a = 0; a < 2; ++a)
; #pragma unroll
;             for (int b = 0; b < 2; ++b)
; #pragma unroll
;                 for (int m = 0; m < 4; ++m)
; #pragma unroll
;                     for (int n = 0; n < 2; ++n) acc[a][b][m][n] = (f32x4){0.f, 0.f, 0.f, 0.f};
.LBB0_1320:
	s_mov_b32 s55, s28
	s_add_i32 s28, s28, 1
	s_mov_b64 s[18:19], s[6:7]
	s_lshl_b32 s6, s28, 4
	s_mov_b32 s56, s54
	s_or_b32 s54, s6, s2
	s_mul_i32 s6, s54, 0x808000
	s_add_u32 s6, s44, s6
	s_addc_u32 s7, s45, 0
	s_cmp_lt_u32 s55, 3
	s_mov_b64 s[20:21], s[16:17]
	s_cselect_b32 s7, s7, s19
	s_cselect_b32 s6, s6, s18
	s_cselect_b32 s17, s5, s21
	s_cselect_b32 s16, s4, s20
	s_add_u32 s18, s18, 0x404080
	s_addc_u32 s19, s19, 0
	s_add_u32 s57, s20, 0x100
	s_addc_u32 s58, s21, 0
	s_mov_b32 s59, -2
	s_cmp_lt_u32 s24, 0x1000
	s_cbranch_scc0 .Lf2_h1first
	ds_read_b128 v[128:131], v156
	ds_read_b128 v[132:135], v156 offset:1024
	ds_read_b128 v[150:153], v156 offset:2048
	ds_read_b128 v[162:165], v156 offset:3072
	ds_read_b128 v[166:169], v157
	ds_read_b128 v[170:173], v157 offset:1024
	ds_read_b128 v[174:177], v157 offset:2048
	ds_read_b128 v[178:181], v157 offset:3072
	s_add_u32 s20, s18, 0xffbfc080
	s_addc_u32 s21, s19, -1
	s_cmpk_eq_i32 s59, 0xfc
	s_cselect_b32 s23, s7, s21
	s_cselect_b32 s22, s6, s20
	s_cselect_b32 s21, s17, s58
	s_cselect_b32 s20, s16, s57
	ds_read_b128 v[182:185], v158
	ds_read_b128 v[186:189], v158 offset:1024
	ds_read_b128 v[190:193], v158 offset:2048
	ds_read_b128 v[194:197], v158 offset:3072
	ds_read_b128 v[198:201], v158 offset:4096
	ds_read_b128 v[202:205], v158 offset:5120
	ds_read_b128 v[206:209], v158 offset:6144
	ds_read_b128 v[210:213], v158 offset:7168
	s_add_i32 m0, s24, 0xc000
	s_nop 0
	global_load_lds_dwordx4 v136, s[18:19]
	s_add_i32 m0, s24, 0xe000
	s_nop 0
	global_load_lds_dwordx4 v140, s[18:19]
	s_waitcnt lgkmcnt(0)
	s_setprio 1
	v_mfma_f32_16x16x32_bf16 v[124:127], v[128:131], v[182:185], 0
	v_mfma_f32_16x16x32_bf16 v[124:127], v[132:135], v[186:189], v[124:127]
	v_mfma_f32_16x16x32_bf16 v[120:123], v[150:153], v[182:185], 0
	v_mfma_f32_16x16x32_bf16 v[120:123], v[162:165], v[186:189], v[120:123]
	v_mfma_f32_16x16x32_bf16 v[68:71], v[166:169], v[182:185], 0
	v_mfma_f32_16x16x32_bf16 v[68:71], v[170:173], v[186:189], v[68:71]
	v_mfma_f32_16x16x32_bf16 v[64:67], v[174:177], v[182:185], 0
	v_mfma_f32_16x16x32_bf16 v[64:67], v[178:181], v[186:189], v[64:67]
	v_mfma_f32_16x16x32_bf16 v[48:51], v[174:177], v[190:193], 0
	v_mfma_f32_16x16x32_bf16 v[48:51], v[178:181], v[194:197], v[48:51]
	v_mfma_f32_16x16x32_bf16 v[52:55], v[166:169], v[190:193], 0
	v_mfma_f32_16x16x32_bf16 v[52:55], v[170:173], v[194:197], v[52:55]
	v_mfma_f32_16x16x32_bf16 v[112:115], v[150:153], v[190:193], 0
	v_mfma_f32_16x16x32_bf16 v[112:115], v[162:165], v[194:197], v[112:115]
	v_mfma_f32_16x16x32_bf16 v[116:119], v[128:131], v[190:193], 0
	v_mfma_f32_16x16x32_bf16 v[116:119], v[132:135], v[194:197], v[116:119]
	v_mfma_f32_16x16x32_bf16 v[108:111], v[128:131], v[198:201], 0
	v_mfma_f32_16x16x32_bf16 v[108:111], v[132:135], v[202:205], v[108:111]
	v_mfma_f32_16x16x32_bf16 v[104:107], v[150:153], v[198:201], 0
	v_mfma_f32_16x16x32_bf16 v[104:107], v[162:165], v[202:205], v[104:107]
	v_mfma_f32_16x16x32_bf16 v[44:47], v[166:169], v[198:201], 0
	v_mfma_f32_16x16x32_bf16 v[44:47], v[170:173], v[202:205], v[44:47]
	v_mfma_f32_16x16x32_bf16 v[40:43], v[174:177], v[198:201], 0
	v_mfma_f32_16x16x32_bf16 v[40:43], v[178:181], v[202:205], v[40:43]
	v_mfma_f32_16x16x32_bf16 v[32:35], v[174:177], v[206:209], 0
	v_mfma_f32_16x16x32_bf16 v[32:35], v[178:181], v[210:213], v[32:35]
	v_mfma_f32_16x16x32_bf16 v[36:39], v[166:169], v[206:209], 0
	v_mfma_f32_16x16x32_bf16 v[36:39], v[170:173], v[210:213], v[36:39]
	v_mfma_f32_16x16x32_bf16 v[96:99], v[150:153], v[206:209], 0
	v_mfma_f32_16x16x32_bf16 v[96:99], v[162:165], v[210:213], v[96:99]
	v_mfma_f32_16x16x32_bf16 v[100:103], v[128:131], v[206:209], 0
	v_mfma_f32_16x16x32_bf16 v[100:103], v[132:135], v[210:213], v[100:103]
	s_setprio 0
	s_waitcnt vmcnt(8)
	s_barrier
	ds_read_b128 v[182:185], v158 offset:16384
	ds_read_b128 v[186:189], v158 offset:17408
	ds_read_b128 v[190:193], v158 offset:18432
	ds_read_b128 v[194:197], v158 offset:19456
	ds_read_b128 v[198:201], v158 offset:20480
	ds_read_b128 v[202:205], v158 offset:21504
	ds_read_b128 v[206:209], v158 offset:22528
	ds_read_b128 v[210:213], v158 offset:23552
	s_add_u32 vcc_lo, s20, 0x404000
	s_addc_u32 vcc_hi, s21, 0
	s_add_i32 m0, s24, 0x10000
	s_nop 0
	global_load_lds_dwordx4 v138, s[20:21]
	s_add_i32 m0, s24, 0x12000
	s_nop 0
	global_load_lds_dwordx4 v142, s[20:21]
	s_add_i32 m0, s24, 0x14000
	s_nop 0
	global_load_lds_dwordx4 v138, vcc
	s_add_i32 m0, s24, 0x16000
	s_nop 0
	global_load_lds_dwordx4 v142, vcc
	s_mov_b32 m0, s24
	s_nop 0
	global_load_lds_dwordx4 v136, s[22:23]
	s_add_i32 m0, s24, 0x2000
	s_nop 0
	global_load_lds_dwordx4 v140, s[22:23]
	s_waitcnt lgkmcnt(0)
	s_setprio 1
	v_mfma_f32_16x16x32_bf16 v[92:95], v[128:131], v[182:185], 0
	v_mfma_f32_16x16x32_bf16 v[92:95], v[132:135], v[186:189], v[92:95]
	v_mfma_f32_16x16x32_bf16 v[88:91], v[150:153], v[182:185], 0
	v_mfma_f32_16x16x32_bf16 v[88:91], v[162:165], v[186:189], v[88:91]
	v_mfma_f32_16x16x32_bf16 v[28:31], v[166:169], v[182:185], 0
	v_mfma_f32_16x16x32_bf16 v[28:31], v[170:173], v[186:189], v[28:31]
	v_mfma_f32_16x16x32_bf16 v[24:27], v[174:177], v[182:185], 0
	v_mfma_f32_16x16x32_bf16 v[24:27], v[178:181], v[186:189], v[24:27]
	v_mfma_f32_16x16x32_bf16 v[16:19], v[174:177], v[190:193], 0
	v_mfma_f32_16x16x32_bf16 v[16:19], v[178:181], v[194:197], v[16:19]
	v_mfma_f32_16x16x32_bf16 v[20:23], v[166:169], v[190:193], 0
	v_mfma_f32_16x16x32_bf16 v[20:23], v[170:173], v[194:197], v[20:23]
	v_mfma_f32_16x16x32_bf16 v[80:83], v[150:153], v[190:193], 0
	v_mfma_f32_16x16x32_bf16 v[80:83], v[162:165], v[194:197], v[80:83]
	v_mfma_f32_16x16x32_bf16 v[84:87], v[128:131], v[190:193], 0
	v_mfma_f32_16x16x32_bf16 v[84:87], v[132:135], v[194:197], v[84:87]
	v_mfma_f32_16x16x32_bf16 v[76:79], v[128:131], v[198:201], 0
	v_mfma_f32_16x16x32_bf16 v[76:79], v[132:135], v[202:205], v[76:79]
	v_mfma_f32_16x16x32_bf16 v[72:75], v[150:153], v[198:201], 0
	v_mfma_f32_16x16x32_bf16 v[72:75], v[162:165], v[202:205], v[72:75]
	v_mfma_f32_16x16x32_bf16 v[12:15], v[166:169], v[198:201], 0
	v_mfma_f32_16x16x32_bf16 v[12:15], v[170:173], v[202:205], v[12:15]
	v_mfma_f32_16x16x32_bf16 v[8:11], v[174:177], v[198:201], 0
	v_mfma_f32_16x16x32_bf16 v[8:11], v[178:181], v[202:205], v[8:11]
	v_mfma_f32_16x16x32_bf16 v[0:3], v[174:177], v[206:209], 0
	v_mfma_f32_16x16x32_bf16 v[0:3], v[178:181], v[210:213], v[0:3]
	v_mfma_f32_16x16x32_bf16 v[4:7], v[166:169], v[206:209], 0
	v_mfma_f32_16x16x32_bf16 v[4:7], v[170:173], v[210:213], v[4:7]
	v_mfma_f32_16x16x32_bf16 v[56:59], v[150:153], v[206:209], 0
	v_mfma_f32_16x16x32_bf16 v[56:59], v[162:165], v[210:213], v[56:59]
	v_mfma_f32_16x16x32_bf16 v[60:63], v[128:131], v[206:209], 0
	v_mfma_f32_16x16x32_bf16 v[60:63], v[132:135], v[210:213], v[60:63]
	s_setprio 0
	s_waitcnt vmcnt(8)
	s_barrier
; #define PG8_STAGE(bufoff, gbase, voff) do { _Pragma("unroll") for (int _i = 0; _i < 2; ++_i) \
;         __builtin_amdgcn_global_load_lds((const unsigned*)((const char*)(gbase) + (voff)[_i]), (PG8_LAS unsigned*)(lds + (bufoff) + ldsw + _i * 8192), 16, 0, 0); } while (0)
; #define PG8_LDA(dst, b, h) do { _Pragma("unroll") for (int m = 0; m < 4; ++m) _Pragma("unroll") for (int k = 0; k < 2; ++k) dst[m][k] = *(const PG8_LAS bf16x8*)(lds + PG8_SA(b, h) + aoff + m * 2048 + k * 1024); } while (0)
; #define PG8_LDB(dst, b, h) do { _Pragma("unroll") for (int n = 0; n < 2; ++n) _Pragma("unroll") for (int k = 0; k < 2; ++k) dst[n][k] = *(const PG8_LAS bf16x8*)(lds + PG8_SB(b, h) + boff + n * 2048 + k * 1024); } while (0)
; #define PG8_MMA(ai, bj, At, Bt) do { __builtin_amdgcn_s_setprio(1); _Pragma("unroll") for (int m = 0; m < 4; ++m) _Pragma("unroll") for (int n = 0; n < 2; ++n) _Pragma("unroll") for (int k = 0; k < 2; ++k) \
;         acc[ai][bj][m][n] = __builtin_amdgcn_mfma_f32_16x16x32_bf16(Bt[n][k], At[m][k], acc[ai][bj][m][n], 0, 0, 0); __builtin_amdgcn_s_setprio(0); } while (0)
; #define PG8_WAIT_V(n) asm volatile("s_waitcnt vmcnt(" #n ")" ::: "memory")
; #define PG8_WAIT_L(n) asm volatile("s_waitcnt lgkmcnt(" #n ")" ::: "memory")
; #define PG8_BAR __builtin_amdgcn_s_barrier()
; #define PG8_SCHED __builtin_amdgcn_sched_barrier(0)
; template <class Epi, class Sched, bool ALIGN_EPI = false, bool SP2 = false>
; __device__ __forceinline__ void gemm_phase(PG8_LAS unsigned char* lds, const Gemm g, const Sched& S, const Epi& E) {
;     ...
;         for (int t = 0; t < nt; t += 2) {
;             const bool last = (t == nt - 2);
;     ...
;             PG8_LDB(B0, 1, 0); PG8_LDB(B1, 1, 1); PG8_SCHED; PG8_LDA(At, 1, 0); PG8_STAGE(PG8_SA(0, 1), a2 + hstep, voffA);
;             PG8_WAIT_V(8); PG8_WAIT_L(0); PG8_BAR; PG8_MMA(0, 0, At, B0); PG8_MMA(0, 1, At, B1); PG8_BAR; PG8_SCHED;
;             PG8_LDA(At, 1, 1); PG8_STAGE(PG8_SB(1, 0), b3, voffB); PG8_STAGE(PG8_SB(1, 1), b3 + hstep, voffB); PG8_STAGE(PG8_SA(1, 0), a3, voffA);
;             PG8_WAIT_V(8); PG8_WAIT_L(0); PG8_BAR; PG8_MMA(1, 0, At, B0); PG8_MMA(1, 1, At, B1); PG8_BAR; PG8_SCHED;
	ds_read_b128 v[128:131], v159
	ds_read_b128 v[132:135], v159 offset:1024
	ds_read_b128 v[150:153], v159 offset:2048
	ds_read_b128 v[162:165], v159 offset:3072
	ds_read_b128 v[166:169], v160
	ds_read_b128 v[170:173], v160 offset:1024
	ds_read_b128 v[174:177], v160 offset:2048
	ds_read_b128 v[178:181], v160 offset:3072
	ds_read_b128 v[182:185], v158 offset:32768
	ds_read_b128 v[186:189], v158 offset:33792
	ds_read_b128 v[190:193], v158 offset:34816
	ds_read_b128 v[194:197], v158 offset:35840
	ds_read_b128 v[198:201], v158 offset:36864
	ds_read_b128 v[202:205], v158 offset:37888
	ds_read_b128 v[206:209], v158 offset:38912
	ds_read_b128 v[210:213], v158 offset:39936
	s_add_u32 vcc_lo, s22, 0x404000
	s_addc_u32 vcc_hi, s23, 0
	s_add_i32 m0, s24, 0x4000
	s_nop 0
	global_load_lds_dwordx4 v136, vcc
	s_add_i32 m0, s24, 0x6000
	s_nop 0
	global_load_lds_dwordx4 v140, vcc
	s_waitcnt lgkmcnt(0)
	s_setprio 1
	v_mfma_f32_16x16x32_bf16 v[124:127], v[128:131], v[182:185], v[124:127]
	v_mfma_f32_16x16x32_bf16 v[124:127], v[132:135], v[186:189], v[124:127]
	v_mfma_f32_16x16x32_bf16 v[120:123], v[150:153], v[182:185], v[120:123]
	v_mfma_f32_16x16x32_bf16 v[120:123], v[162:165], v[186:189], v[120:123]
	v_mfma_f32_16x16x32_bf16 v[68:71], v[166:169], v[182:185], v[68:71]
	v_mfma_f32_16x16x32_bf16 v[68:71], v[170:173], v[186:189], v[68:71]
	v_mfma_f32_16x16x32_bf16 v[64:67], v[174:177], v[182:185], v[64:67]
	v_mfma_f32_16x16x32_bf16 v[64:67], v[178:181], v[186:189], v[64:67]
	v_mfma_f32_16x16x32_bf16 v[48:51], v[174:177], v[190:193], v[48:51]
	v_mfma_f32_16x16x32_bf16 v[48:51], v[178:181], v[194:197], v[48:51]
	v_mfma_f32_16x16x32_bf16 v[52:55], v[166:169], v[190:193], v[52:55]
	v_mfma_f32_16x16x32_bf16 v[52:55], v[170:173], v[194:197], v[52:55]
	v_mfma_f32_16x16x32_bf16 v[112:115], v[150:153], v[190:193], v[112:115]
	v_mfma_f32_16x16x32_bf16 v[112:115], v[162:165], v[194:197], v[112:115]
	v_mfma_f32_16x16x32_bf16 v[116:119], v[128:131], v[190:193], v[116:119]
	v_mfma_f32_16x16x32_bf16 v[116:119], v[132:135], v[194:197], v[116:119]
	v_mfma_f32_16x16x32_bf16 v[108:111], v[128:131], v[198:201], v[108:111]
	v_mfma_f32_16x16x32_bf16 v[108:111], v[132:135], v[202:205], v[108:111]
	v_mfma_f32_16x16x32_bf16 v[104:107], v[150:153], v[198:201], v[104:107]
	v_mfma_f32_16x16x32_bf16 v[104:107], v[162:165], v[202:205], v[104:107]
	v_mfma_f32_16x16x32_bf16 v[44:47], v[166:169], v[198:201], v[44:47]
	v_mfma_f32_16x16x32_bf16 v[44:47], v[170:173], v[202:205], v[44:47]
	v_mfma_f32_16x16x32_bf16 v[40:43], v[174:177], v[198:201], v[40:43]
	v_mfma_f32_16x16x32_bf16 v[40:43], v[178:181], v[202:205], v[40:43]
	v_mfma_f32_16x16x32_bf16 v[32:35], v[174:177], v[206:209], v[32:35]
	v_mfma_f32_16x16x32_bf16 v[32:35], v[178:181], v[210:213], v[32:35]
	v_mfma_f32_16x16x32_bf16 v[36:39], v[166:169], v[206:209], v[36:39]
	v_mfma_f32_16x16x32_bf16 v[36:39], v[170:173], v[210:213], v[36:39]
	v_mfma_f32_16x16x32_bf16 v[96:99], v[150:153], v[206:209], v[96:99]
	v_mfma_f32_16x16x32_bf16 v[96:99], v[162:165], v[210:213], v[96:99]
	v_mfma_f32_16x16x32_bf16 v[100:103], v[128:131], v[206:209], v[100:103]
	v_mfma_f32_16x16x32_bf16 v[100:103], v[132:135], v[210:213], v[100:103]
	s_setprio 0
	s_waitcnt vmcnt(8)
	s_barrier
	ds_read_b128 v[182:185], v158 offset:49152
	ds_read_b128 v[186:189], v158 offset:50176
	ds_read_b128 v[190:193], v158 offset:51200
	ds_read_b128 v[194:197], v158 offset:52224
	ds_read_b128 v[198:201], v158 offset:53248
	ds_read_b128 v[202:205], v158 offset:54272
	ds_read_b128 v[206:209], v158 offset:55296
	ds_read_b128 v[210:213], v158 offset:56320
	s_add_u32 s60, s20, 0x80
	s_addc_u32 s61, s21, 0
	s_add_u32 vcc_lo, s60, 0x404000
	s_addc_u32 vcc_hi, s61, 0
	s_add_i32 m0, s24, 0x18000
	s_nop 0
	global_load_lds_dwordx4 v138, s[60:61]
	s_add_i32 m0, s24, 0x1a000
	s_nop 0
	global_load_lds_dwordx4 v142, s[60:61]
	s_add_i32 m0, s24, 0x1c000
	s_nop 0
	global_load_lds_dwordx4 v138, vcc
	s_add_i32 m0, s24, 0x1e000
	s_nop 0
	global_load_lds_dwordx4 v142, vcc
	s_add_u32 s60, s22, 0x80
	s_addc_u32 s61, s23, 0
	s_add_i32 m0, s24, 0x8000
	s_nop 0
	global_load_lds_dwordx4 v136, s[60:61]
	s_add_i32 m0, s24, 0xa000
	s_nop 0
	global_load_lds_dwordx4 v140, s[60:61]
	s_waitcnt lgkmcnt(0)
	s_setprio 1
	v_mfma_f32_16x16x32_bf16 v[92:95], v[128:131], v[182:185], v[92:95]
	v_mfma_f32_16x16x32_bf16 v[92:95], v[132:135], v[186:189], v[92:95]
	v_mfma_f32_16x16x32_bf16 v[88:91], v[150:153], v[182:185], v[88:91]
	v_mfma_f32_16x16x32_bf16 v[88:91], v[162:165], v[186:189], v[88:91]
	v_mfma_f32_16x16x32_bf16 v[28:31], v[166:169], v[182:185], v[28:31]
	v_mfma_f32_16x16x32_bf16 v[28:31], v[170:173], v[186:189], v[28:31]
	v_mfma_f32_16x16x32_bf16 v[24:27], v[174:177], v[182:185], v[24:27]
	v_mfma_f32_16x16x32_bf16 v[24:27], v[178:181], v[186:189], v[24:27]
	v_mfma_f32_16x16x32_bf16 v[16:19], v[174:177], v[190:193], v[16:19]
	v_mfma_f32_16x16x32_bf16 v[16:19], v[178:181], v[194:197], v[16:19]
	v_mfma_f32_16x16x32_bf16 v[20:23], v[166:169], v[190:193], v[20:23]
	v_mfma_f32_16x16x32_bf16 v[20:23], v[170:173], v[194:197], v[20:23]
	v_mfma_f32_16x16x32_bf16 v[80:83], v[150:153], v[190:193], v[80:83]
	v_mfma_f32_16x16x32_bf16 v[80:83], v[162:165], v[194:197], v[80:83]
	v_mfma_f32_16x16x32_bf16 v[84:87], v[128:131], v[190:193], v[84:87]
	v_mfma_f32_16x16x32_bf16 v[84:87], v[132:135], v[194:197], v[84:87]
	v_mfma_f32_16x16x32_bf16 v[76:79], v[128:131], v[198:201], v[76:79]
	v_mfma_f32_16x16x32_bf16 v[76:79], v[132:135], v[202:205], v[76:79]
	v_mfma_f32_16x16x32_bf16 v[72:75], v[150:153], v[198:201], v[72:75]
	v_mfma_f32_16x16x32_bf16 v[72:75], v[162:165], v[202:205], v[72:75]
	v_mfma_f32_16x16x32_bf16 v[12:15], v[166:169], v[198:201], v[12:15]
	v_mfma_f32_16x16x32_bf16 v[12:15], v[170:173], v[202:205], v[12:15]
	v_mfma_f32_16x16x32_bf16 v[8:11], v[174:177], v[198:201], v[8:11]
	v_mfma_f32_16x16x32_bf16 v[8:11], v[178:181], v[202:205], v[8:11]
	v_mfma_f32_16x16x32_bf16 v[0:3], v[174:177], v[206:209], v[0:3]
	v_mfma_f32_16x16x32_bf16 v[0:3], v[178:181], v[210:213], v[0:3]
	v_mfma_f32_16x16x32_bf16 v[4:7], v[166:169], v[206:209], v[4:7]
	v_mfma_f32_16x16x32_bf16 v[4:7], v[170:173], v[210:213], v[4:7]
	v_mfma_f32_16x16x32_bf16 v[56:59], v[150:153], v[206:209], v[56:59]
	v_mfma_f32_16x16x32_bf16 v[56:59], v[162:165], v[210:213], v[56:59]
	v_mfma_f32_16x16x32_bf16 v[60:63], v[128:131], v[206:209], v[60:63]
	v_mfma_f32_16x16x32_bf16 v[60:63], v[132:135], v[210:213], v[60:63]
	s_setprio 0
	s_waitcnt vmcnt(8)
	s_barrier
	s_add_i32 s59, s59, 2
	s_add_u32 s18, s18, 0x100
	s_addc_u32 s19, s19, 0
	s_add_u32 s57, s57, 0x100
	s_addc_u32 s58, s58, 0
	s_cmpk_gt_u32 s59, 0xfd

; #define PG8_STAGE(bufoff, gbase, voff) do { _Pragma("unroll") for (int _i = 0; _i < 2; ++_i) \
;         __builtin_amdgcn_global_load_lds((const unsigned*)((const char*)(gbase) + (voff)[_i]), (PG8_LAS unsigned*)(lds + (bufoff) + ldsw + _i * 8192), 16, 0, 0); } while (0)
; #define PG8_LDA(dst, b, h) do { _Pragma("unroll") for (int m = 0; m < 4; ++m) _Pragma("unroll") for (int k = 0; k < 2; ++k) dst[m][k] = *(const PG8_LAS bf16x8*)(lds + PG8_SA(b, h) + aoff + m * 2048 + k * 1024); } while (0)
; #define PG8_LDB(dst, b, h) do { _Pragma("unroll") for (int n = 0; n < 2; ++n) _Pragma("unroll") for (int k = 0; k < 2; ++k) dst[n][k] = *(const PG8_LAS bf16x8*)(lds + PG8_SB(b, h) + boff + n * 2048 + k * 1024); } while (0)
; #define PG8_MMA(ai, bj, At, Bt) do { __builtin_amdgcn_s_setprio(1); _Pragma("unroll") for (int m = 0; m < 4; ++m) _Pragma("unroll") for (int n = 0; n < 2; ++n) _Pragma("unroll") for (int k = 0; k < 2; ++k) \
;         acc[ai][bj][m][n] = __builtin_amdgcn_mfma_f32_16x16x32_bf16(Bt[n][k], At[m][k], acc[ai][bj][m][n], 0, 0, 0); __builtin_amdgcn_s_setprio(0); } while (0)
; #define PG8_WAIT_V(n) asm volatile("s_waitcnt vmcnt(" #n ")" ::: "memory")
; #define PG8_WAIT_L(n) asm volatile("s_waitcnt lgkmcnt(" #n ")" ::: "memory")
; #define PG8_BAR __builtin_amdgcn_s_barrier()
; #define PG8_SCHED __builtin_amdgcn_sched_barrier(0)
; template <class Epi, class Sched, bool ALIGN_EPI = false, bool SP2 = false>
; __device__ __forceinline__ void gemm_phase(PG8_LAS unsigned char* lds, const Gemm g, const Sched& S, const Epi& E) {
;     ...
;             PG8_LDB(B0, 0, 0); PG8_LDB(B1, 0, 1); PG8_SCHED; PG8_LDA(At, 0, 0); PG8_STAGE(PG8_SA(1, 1), a1 + hstep, voffA);
;             PG8_WAIT_V(8); PG8_WAIT_L(0); PG8_BAR; PG8_MMA(0, 0, At, B0); PG8_MMA(0, 1, At, B1); PG8_BAR; PG8_SCHED;
;             PG8_LDA(At, 0, 1); PG8_STAGE(PG8_SB(0, 0), b2, voffB); PG8_STAGE(PG8_SB(0, 1), b2 + hstep, voffB); PG8_STAGE(PG8_SA(0, 0), a2, voffA);
;             PG8_WAIT_V(8); PG8_WAIT_L(0); PG8_BAR; PG8_MMA(1, 0, At, B0); PG8_MMA(1, 1, At, B1); PG8_BAR; PG8_SCHED;
.Lf2_h1first:
	ds_read_b128 v[128:131], v156
	ds_read_b128 v[132:135], v156 offset:1024
	ds_read_b128 v[150:153], v156 offset:2048
	ds_read_b128 v[162:165], v156 offset:3072
	ds_read_b128 v[166:169], v157
	ds_read_b128 v[170:173], v157 offset:1024
	ds_read_b128 v[174:177], v157 offset:2048
	ds_read_b128 v[178:181], v157 offset:3072
	s_add_u32 s20, s18, 0xffbfc080
	s_addc_u32 s21, s19, -1
	s_cmpk_eq_i32 s59, 0xfc
	s_cselect_b32 s23, s7, s21
	s_cselect_b32 s22, s6, s20
	s_cselect_b32 s21, s17, s58
	s_cselect_b32 s20, s16, s57
	ds_read_b128 v[182:185], v158
	ds_read_b128 v[186:189], v158 offset:1024
	ds_read_b128 v[190:193], v158 offset:2048
	ds_read_b128 v[194:197], v158 offset:3072
	ds_read_b128 v[198:201], v158 offset:4096
	ds_read_b128 v[202:205], v158 offset:5120
	ds_read_b128 v[206:209], v158 offset:6144
	ds_read_b128 v[210:213], v158 offset:7168
	s_add_i32 m0, s24, 0xc000
	s_nop 0
	global_load_lds_dwordx4 v136, s[18:19]
	s_add_i32 m0, s24, 0xe000
	s_nop 0
	global_load_lds_dwordx4 v140, s[18:19]
	s_sleep 2
	s_waitcnt lgkmcnt(0)
	s_waitcnt vmcnt(8)
	s_barrier
	s_setprio 2
	v_mfma_f32_16x16x32_bf16 v[124:127], v[128:131], v[182:185], 0
	v_mfma_f32_16x16x32_bf16 v[124:127], v[132:135], v[186:189], v[124:127]
	v_mfma_f32_16x16x32_bf16 v[120:123], v[150:153], v[182:185], 0
	v_mfma_f32_16x16x32_bf16 v[120:123], v[162:165], v[186:189], v[120:123]
	v_mfma_f32_16x16x32_bf16 v[68:71], v[166:169], v[182:185], 0
	v_mfma_f32_16x16x32_bf16 v[68:71], v[170:173], v[186:189], v[68:71]
	v_mfma_f32_16x16x32_bf16 v[64:67], v[174:177], v[182:185], 0
	v_mfma_f32_16x16x32_bf16 v[64:67], v[178:181], v[186:189], v[64:67]
	v_mfma_f32_16x16x32_bf16 v[48:51], v[174:177], v[190:193], 0
	v_mfma_f32_16x16x32_bf16 v[48:51], v[178:181], v[194:197], v[48:51]
	v_mfma_f32_16x16x32_bf16 v[52:55], v[166:169], v[190:193], 0
	v_mfma_f32_16x16x32_bf16 v[52:55], v[170:173], v[194:197], v[52:55]
	v_mfma_f32_16x16x32_bf16 v[112:115], v[150:153], v[190:193], 0
	v_mfma_f32_16x16x32_bf16 v[112:115], v[162:165], v[194:197], v[112:115]
	v_mfma_f32_16x16x32_bf16 v[116:119], v[128:131], v[190:193], 0
	v_mfma_f32_16x16x32_bf16 v[116:119], v[132:135], v[194:197], v[116:119]
	v_mfma_f32_16x16x32_bf16 v[108:111], v[128:131], v[198:201], 0
	v_mfma_f32_16x16x32_bf16 v[108:111], v[132:135], v[202:205], v[108:111]
	v_mfma_f32_16x16x32_bf16 v[104:107], v[150:153], v[198:201], 0
	v_mfma_f32_16x16x32_bf16 v[104:107], v[162:165], v[202:205], v[104:107]
	v_mfma_f32_16x16x32_bf16 v[44:47], v[166:169], v[198:201], 0
	v_mfma_f32_16x16x32_bf16 v[44:47], v[170:173], v[202:205], v[44:47]
	v_mfma_f32_16x16x32_bf16 v[40:43], v[174:177], v[198:201], 0
	v_mfma_f32_16x16x32_bf16 v[40:43], v[178:181], v[202:205], v[40:43]
	v_mfma_f32_16x16x32_bf16 v[32:35], v[174:177], v[206:209], 0
	v_mfma_f32_16x16x32_bf16 v[32:35], v[178:181], v[210:213], v[32:35]
	v_mfma_f32_16x16x32_bf16 v[36:39], v[166:169], v[206:209], 0
	v_mfma_f32_16x16x32_bf16 v[36:39], v[170:173], v[210:213], v[36:39]
	v_mfma_f32_16x16x32_bf16 v[96:99], v[150:153], v[206:209], 0
	v_mfma_f32_16x16x32_bf16 v[96:99], v[162:165], v[210:213], v[96:99]
	v_mfma_f32_16x16x32_bf16 v[100:103], v[128:131], v[206:209], 0
	v_mfma_f32_16x16x32_bf16 v[100:103], v[132:135], v[210:213], v[100:103]
	s_setprio 0
	ds_read_b128 v[182:185], v158 offset:16384
	ds_read_b128 v[186:189], v158 offset:17408
	ds_read_b128 v[190:193], v158 offset:18432
	ds_read_b128 v[194:197], v158 offset:19456
	ds_read_b128 v[198:201], v158 offset:20480
	ds_read_b128 v[202:205], v158 offset:21504
	ds_read_b128 v[206:209], v158 offset:22528
	ds_read_b128 v[210:213], v158 offset:23552
	s_add_u32 vcc_lo, s20, 0x404000
	s_addc_u32 vcc_hi, s21, 0
	s_add_i32 m0, s24, 0x10000
	s_nop 0
	global_load_lds_dwordx4 v138, s[20:21]
	s_add_i32 m0, s24, 0x12000
	s_nop 0
	global_load_lds_dwordx4 v142, s[20:21]
	s_add_i32 m0, s24, 0x14000
	s_nop 0
	global_load_lds_dwordx4 v138, vcc
	s_add_i32 m0, s24, 0x16000
	s_nop 0
	global_load_lds_dwordx4 v142, vcc
	s_mov_b32 m0, s24
	s_nop 0
	global_load_lds_dwordx4 v136, s[22:23]
	s_add_i32 m0, s24, 0x2000
	s_nop 0
	global_load_lds_dwordx4 v140, s[22:23]
	s_sleep 2
	s_waitcnt lgkmcnt(0)
	s_waitcnt vmcnt(8)
	s_barrier
	s_setprio 2
	v_mfma_f32_16x16x32_bf16 v[92:95], v[128:131], v[182:185], 0
	v_mfma_f32_16x16x32_bf16 v[92:95], v[132:135], v[186:189], v[92:95]
	v_mfma_f32_16x16x32_bf16 v[88:91], v[150:153], v[182:185], 0
	v_mfma_f32_16x16x32_bf16 v[88:91], v[162:165], v[186:189], v[88:91]
	v_mfma_f32_16x16x32_bf16 v[28:31], v[166:169], v[182:185], 0
	v_mfma_f32_16x16x32_bf16 v[28:31], v[170:173], v[186:189], v[28:31]
	v_mfma_f32_16x16x32_bf16 v[24:27], v[174:177], v[182:185], 0
	v_mfma_f32_16x16x32_bf16 v[24:27], v[178:181], v[186:189], v[24:27]
	v_mfma_f32_16x16x32_bf16 v[16:19], v[174:177], v[190:193], 0
	v_mfma_f32_16x16x32_bf16 v[16:19], v[178:181], v[194:197], v[16:19]
	v_mfma_f32_16x16x32_bf16 v[20:23], v[166:169], v[190:193], 0
	v_mfma_f32_16x16x32_bf16 v[20:23], v[170:173], v[194:197], v[20:23]
	v_mfma_f32_16x16x32_bf16 v[80:83], v[150:153], v[190:193], 0
	v_mfma_f32_16x16x32_bf16 v[80:83], v[162:165], v[194:197], v[80:83]
	v_mfma_f32_16x16x32_bf16 v[84:87], v[128:131], v[190:193], 0
	v_mfma_f32_16x16x32_bf16 v[84:87], v[132:135], v[194:197], v[84:87]
	v_mfma_f32_16x16x32_bf16 v[76:79], v[128:131], v[198:201], 0
	v_mfma_f32_16x16x32_bf16 v[76:79], v[132:135], v[202:205], v[76:79]
	v_mfma_f32_16x16x32_bf16 v[72:75], v[150:153], v[198:201], 0
	v_mfma_f32_16x16x32_bf16 v[72:75], v[162:165], v[202:205], v[72:75]
	v_mfma_f32_16x16x32_bf16 v[12:15], v[166:169], v[198:201], 0
	v_mfma_f32_16x16x32_bf16 v[12:15], v[170:173], v[202:205], v[12:15]
; #define PG8_STAGE(bufoff, gbase, voff) do { _Pragma("unroll") for (int _i = 0; _i < 2; ++_i) \
;         __builtin_amdgcn_global_load_lds((const unsigned*)((const char*)(gbase) + (voff)[_i]), (PG8_LAS unsigned*)(lds + (bufoff) + ldsw + _i * 8192), 16, 0, 0); } while (0)
; #define PG8_LDA(dst, b, h) do { _Pragma("unroll") for (int m = 0; m < 4; ++m) _Pragma("unroll") for (int k = 0; k < 2; ++k) dst[m][k] = *(const PG8_LAS bf16x8*)(lds + PG8_SA(b, h) + aoff + m * 2048 + k * 1024); } while (0)
; #define PG8_LDB(dst, b, h) do { _Pragma("unroll") for (int n = 0; n < 2; ++n) _Pragma("unroll") for (int k = 0; k < 2; ++k) dst[n][k] = *(const PG8_LAS bf16x8*)(lds + PG8_SB(b, h) + boff + n * 2048 + k * 1024); } while (0)
; #define PG8_MMA(ai, bj, At, Bt) do { __builtin_amdgcn_s_setprio(1); _Pragma("unroll") for (int m = 0; m < 4; ++m) _Pragma("unroll") for (int n = 0; n < 2; ++n) _Pragma("unroll") for (int k = 0; k < 2; ++k) \
;         acc[ai][bj][m][n] = __builtin_amdgcn_mfma_f32_16x16x32_bf16(Bt[n][k], At[m][k], acc[ai][bj][m][n], 0, 0, 0); __builtin_amdgcn_s_setprio(0); } while (0)
; #define PG8_WAIT_V(n) asm volatile("s_waitcnt vmcnt(" #n ")" ::: "memory")
; #define PG8_WAIT_L(n) asm volatile("s_waitcnt lgkmcnt(" #n ")" ::: "memory")
; #define PG8_BAR __builtin_amdgcn_s_barrier()
; #define PG8_SCHED __builtin_amdgcn_sched_barrier(0)
; template <class Epi, class Sched, bool ALIGN_EPI = false, bool SP2 = false>
; __device__ __forceinline__ void gemm_phase(PG8_LAS unsigned char* lds, const Gemm g, const Sched& S, const Epi& E) {
;     ...
;             PG8_WAIT_V(8); PG8_WAIT_L(0); PG8_BAR; PG8_MMA(1, 0, At, B0); PG8_MMA(1, 1, At, B1); PG8_BAR; PG8_SCHED;
;             PG8_LDB(B0, 1, 0); PG8_LDB(B1, 1, 1); PG8_SCHED; PG8_LDA(At, 1, 0); PG8_STAGE(PG8_SA(0, 1), a2 + hstep, voffA);
;             PG8_WAIT_V(8); PG8_WAIT_L(0); PG8_BAR; PG8_MMA(0, 0, At, B0); PG8_MMA(0, 1, At, B1); PG8_BAR; PG8_SCHED;
;             PG8_LDA(At, 1, 1); PG8_STAGE(PG8_SB(1, 0), b3, voffB); PG8_STAGE(PG8_SB(1, 1), b3 + hstep, voffB); PG8_STAGE(PG8_SA(1, 0), a3, voffA);
	v_mfma_f32_16x16x32_bf16 v[8:11], v[174:177], v[198:201], 0
	v_mfma_f32_16x16x32_bf16 v[8:11], v[178:181], v[202:205], v[8:11]
	v_mfma_f32_16x16x32_bf16 v[0:3], v[174:177], v[206:209], 0
	v_mfma_f32_16x16x32_bf16 v[0:3], v[178:181], v[210:213], v[0:3]
	v_mfma_f32_16x16x32_bf16 v[4:7], v[166:169], v[206:209], 0
	v_mfma_f32_16x16x32_bf16 v[4:7], v[170:173], v[210:213], v[4:7]
	v_mfma_f32_16x16x32_bf16 v[56:59], v[150:153], v[206:209], 0
	v_mfma_f32_16x16x32_bf16 v[56:59], v[162:165], v[210:213], v[56:59]
	v_mfma_f32_16x16x32_bf16 v[60:63], v[128:131], v[206:209], 0
	v_mfma_f32_16x16x32_bf16 v[60:63], v[132:135], v[210:213], v[60:63]
	s_setprio 0
	ds_read_b128 v[128:131], v159
	ds_read_b128 v[132:135], v159 offset:1024
	ds_read_b128 v[150:153], v159 offset:2048
	ds_read_b128 v[162:165], v159 offset:3072
	ds_read_b128 v[166:169], v160
	ds_read_b128 v[170:173], v160 offset:1024
	ds_read_b128 v[174:177], v160 offset:2048
	ds_read_b128 v[178:181], v160 offset:3072
	ds_read_b128 v[182:185], v158 offset:32768
	ds_read_b128 v[186:189], v158 offset:33792
	ds_read_b128 v[190:193], v158 offset:34816
	ds_read_b128 v[194:197], v158 offset:35840
	ds_read_b128 v[198:201], v158 offset:36864
	ds_read_b128 v[202:205], v158 offset:37888
	ds_read_b128 v[206:209], v158 offset:38912
	ds_read_b128 v[210:213], v158 offset:39936
	s_add_u32 vcc_lo, s22, 0x404000
	s_addc_u32 vcc_hi, s23, 0
	s_add_i32 m0, s24, 0x4000
	s_nop 0
	global_load_lds_dwordx4 v136, vcc
	s_add_i32 m0, s24, 0x6000
	s_nop 0
	global_load_lds_dwordx4 v140, vcc
	s_sleep 2
	s_waitcnt lgkmcnt(0)
	s_waitcnt vmcnt(8)
	s_barrier
	s_setprio 2
	v_mfma_f32_16x16x32_bf16 v[124:127], v[128:131], v[182:185], v[124:127]
	v_mfma_f32_16x16x32_bf16 v[124:127], v[132:135], v[186:189], v[124:127]
	v_mfma_f32_16x16x32_bf16 v[120:123], v[150:153], v[182:185], v[120:123]
	v_mfma_f32_16x16x32_bf16 v[120:123], v[162:165], v[186:189], v[120:123]
	v_mfma_f32_16x16x32_bf16 v[68:71], v[166:169], v[182:185], v[68:71]
	v_mfma_f32_16x16x32_bf16 v[68:71], v[170:173], v[186:189], v[68:71]
	v_mfma_f32_16x16x32_bf16 v[64:67], v[174:177], v[182:185], v[64:67]
	v_mfma_f32_16x16x32_bf16 v[64:67], v[178:181], v[186:189], v[64:67]
	v_mfma_f32_16x16x32_bf16 v[48:51], v[174:177], v[190:193], v[48:51]
	v_mfma_f32_16x16x32_bf16 v[48:51], v[178:181], v[194:197], v[48:51]
	v_mfma_f32_16x16x32_bf16 v[52:55], v[166:169], v[190:193], v[52:55]
	v_mfma_f32_16x16x32_bf16 v[52:55], v[170:173], v[194:197], v[52:55]
	v_mfma_f32_16x16x32_bf16 v[112:115], v[150:153], v[190:193], v[112:115]
	v_mfma_f32_16x16x32_bf16 v[112:115], v[162:165], v[194:197], v[112:115]
	v_mfma_f32_16x16x32_bf16 v[116:119], v[128:131], v[190:193], v[116:119]
	v_mfma_f32_16x16x32_bf16 v[116:119], v[132:135], v[194:197], v[116:119]
	v_mfma_f32_16x16x32_bf16 v[108:111], v[128:131], v[198:201], v[108:111]
	v_mfma_f32_16x16x32_bf16 v[108:111], v[132:135], v[202:205], v[108:111]
	v_mfma_f32_16x16x32_bf16 v[104:107], v[150:153], v[198:201], v[104:107]
	v_mfma_f32_16x16x32_bf16 v[104:107], v[162:165], v[202:205], v[104:107]
	v_mfma_f32_16x16x32_bf16 v[44:47], v[166:169], v[198:201], v[44:47]
	v_mfma_f32_16x16x32_bf16 v[44:47], v[170:173], v[202:205], v[44:47]
	v_mfma_f32_16x16x32_bf16 v[40:43], v[174:177], v[198:201], v[40:43]
	v_mfma_f32_16x16x32_bf16 v[40:43], v[178:181], v[202:205], v[40:43]
	v_mfma_f32_16x16x32_bf16 v[32:35], v[174:177], v[206:209], v[32:35]
	v_mfma_f32_16x16x32_bf16 v[32:35], v[178:181], v[210:213], v[32:35]
	v_mfma_f32_16x16x32_bf16 v[36:39], v[166:169], v[206:209], v[36:39]
	v_mfma_f32_16x16x32_bf16 v[36:39], v[170:173], v[210:213], v[36:39]
	v_mfma_f32_16x16x32_bf16 v[96:99], v[150:153], v[206:209], v[96:99]
	v_mfma_f32_16x16x32_bf16 v[96:99], v[162:165], v[210:213], v[96:99]
	v_mfma_f32_16x16x32_bf16 v[100:103], v[128:131], v[206:209], v[100:103]
	v_mfma_f32_16x16x32_bf16 v[100:103], v[132:135], v[210:213], v[100:103]
	s_setprio 0
	ds_read_b128 v[182:185], v158 offset:49152
	ds_read_b128 v[186:189], v158 offset:50176
	ds_read_b128 v[190:193], v158 offset:51200
	ds_read_b128 v[194:197], v158 offset:52224
	ds_read_b128 v[198:201], v158 offset:53248
	ds_read_b128 v[202:205], v158 offset:54272
	ds_read_b128 v[206:209], v158 offset:55296
	ds_read_b128 v[210:213], v158 offset:56320
	s_add_u32 s60, s20, 0x80
	s_addc_u32 s61, s21, 0
	s_add_u32 vcc_lo, s60, 0x404000
	s_addc_u32 vcc_hi, s61, 0
	s_add_i32 m0, s24, 0x18000
	s_nop 0
	global_load_lds_dwordx4 v138, s[60:61]
	s_add_i32 m0, s24, 0x1a000
	s_nop 0
	global_load_lds_dwordx4 v142, s[60:61]
	s_add_i32 m0, s24, 0x1c000
	s_nop 0
	global_load_lds_dwordx4 v138, vcc
	s_add_i32 m0, s24, 0x1e000
	s_nop 0
	global_load_lds_dwordx4 v142, vcc
	s_add_u32 s60, s22, 0x80
	s_addc_u32 s61, s23, 0
	s_add_i32 m0, s24, 0x8000
	s_nop 0
	global_load_lds_dwordx4 v136, s[60:61]
	s_add_i32 m0, s24, 0xa000
	s_nop 0
	global_load_lds_dwordx4 v140, s[60:61]
	s_sleep 2
	s_waitcnt lgkmcnt(0)
	s_waitcnt vmcnt(8)
	s_barrier
; #define PG8_STAGE(bufoff, gbase, voff) do { _Pragma("unroll") for (int _i = 0; _i < 2; ++_i) \
;         __builtin_amdgcn_global_load_lds((const unsigned*)((const char*)(gbase) + (voff)[_i]), (PG8_LAS unsigned*)(lds + (bufoff) + ldsw + _i * 8192), 16, 0, 0); } while (0)
; #define PG8_LDA(dst, b, h) do { _Pragma("unroll") for (int m = 0; m < 4; ++m) _Pragma("unroll") for (int k = 0; k < 2; ++k) dst[m][k] = *(const PG8_LAS bf16x8*)(lds + PG8_SA(b, h) + aoff + m * 2048 + k * 1024); } while (0)
; #define PG8_MMA(ai, bj, At, Bt) do { __builtin_amdgcn_s_setprio(1); _Pragma("unroll") for (int m = 0; m < 4; ++m) _Pragma("unroll") for (int n = 0; n < 2; ++n) _Pragma("unroll") for (int k = 0; k < 2; ++k) \
;         acc[ai][bj][m][n] = __builtin_amdgcn_mfma_f32_16x16x32_bf16(Bt[n][k], At[m][k], acc[ai][bj][m][n], 0, 0, 0); __builtin_amdgcn_s_setprio(0); } while (0)
; #define PG8_WAIT_V(n) asm volatile("s_waitcnt vmcnt(" #n ")" ::: "memory")
; #define PG8_WAIT_L(n) asm volatile("s_waitcnt lgkmcnt(" #n ")" ::: "memory")
; #define PG8_BAR __builtin_amdgcn_s_barrier()
; #define PG8_SCHED __builtin_amdgcn_sched_barrier(0)
; template <class Epi, class Sched, bool ALIGN_EPI = false, bool SP2 = false>
; __device__ __forceinline__ void gemm_phase(PG8_LAS unsigned char* lds, const Gemm g, const Sched& S, const Epi& E) {
;     ...
;         for (int t = 0; t < nt; t += 2) {
;             const bool last = (t == nt - 2);
;     ...
;             PG8_LDA(At, 1, 1); PG8_STAGE(PG8_SB(1, 0), b3, voffB); PG8_STAGE(PG8_SB(1, 1), b3 + hstep, voffB); PG8_STAGE(PG8_SA(1, 0), a3, voffA);
;             PG8_WAIT_V(8); PG8_WAIT_L(0); PG8_BAR; PG8_MMA(1, 0, At, B0); PG8_MMA(1, 1, At, B1); PG8_BAR; PG8_SCHED;
	s_setprio 2
	v_mfma_f32_16x16x32_bf16 v[92:95], v[128:131], v[182:185], v[92:95]
	v_mfma_f32_16x16x32_bf16 v[92:95], v[132:135], v[186:189], v[92:95]
	v_mfma_f32_16x16x32_bf16 v[88:91], v[150:153], v[182:185], v[88:91]
	v_mfma_f32_16x16x32_bf16 v[88:91], v[162:165], v[186:189], v[88:91]
	v_mfma_f32_16x16x32_bf16 v[28:31], v[166:169], v[182:185], v[28:31]
	v_mfma_f32_16x16x32_bf16 v[28:31], v[170:173], v[186:189], v[28:31]
	v_mfma_f32_16x16x32_bf16 v[24:27], v[174:177], v[182:185], v[24:27]
	v_mfma_f32_16x16x32_bf16 v[24:27], v[178:181], v[186:189], v[24:27]
	v_mfma_f32_16x16x32_bf16 v[16:19], v[174:177], v[190:193], v[16:19]
	v_mfma_f32_16x16x32_bf16 v[16:19], v[178:181], v[194:197], v[16:19]
	v_mfma_f32_16x16x32_bf16 v[20:23], v[166:169], v[190:193], v[20:23]
	v_mfma_f32_16x16x32_bf16 v[20:23], v[170:173], v[194:197], v[20:23]
	v_mfma_f32_16x16x32_bf16 v[80:83], v[150:153], v[190:193], v[80:83]
	v_mfma_f32_16x16x32_bf16 v[80:83], v[162:165], v[194:197], v[80:83]
	v_mfma_f32_16x16x32_bf16 v[84:87], v[128:131], v[190:193], v[84:87]
	v_mfma_f32_16x16x32_bf16 v[84:87], v[132:135], v[194:197], v[84:87]
	v_mfma_f32_16x16x32_bf16 v[76:79], v[128:131], v[198:201], v[76:79]
	v_mfma_f32_16x16x32_bf16 v[76:79], v[132:135], v[202:205], v[76:79]
	v_mfma_f32_16x16x32_bf16 v[72:75], v[150:153], v[198:201], v[72:75]
	v_mfma_f32_16x16x32_bf16 v[72:75], v[162:165], v[202:205], v[72:75]
	v_mfma_f32_16x16x32_bf16 v[12:15], v[166:169], v[198:201], v[12:15]
	v_mfma_f32_16x16x32_bf16 v[12:15], v[170:173], v[202:205], v[12:15]
	v_mfma_f32_16x16x32_bf16 v[8:11], v[174:177], v[198:201], v[8:11]
	v_mfma_f32_16x16x32_bf16 v[8:11], v[178:181], v[202:205], v[8:11]
	v_mfma_f32_16x16x32_bf16 v[0:3], v[174:177], v[206:209], v[0:3]
	v_mfma_f32_16x16x32_bf16 v[0:3], v[178:181], v[210:213], v[0:3]
	v_mfma_f32_16x16x32_bf16 v[4:7], v[166:169], v[206:209], v[4:7]
	v_mfma_f32_16x16x32_bf16 v[4:7], v[170:173], v[210:213], v[4:7]
	v_mfma_f32_16x16x32_bf16 v[56:59], v[150:153], v[206:209], v[56:59]
	v_mfma_f32_16x16x32_bf16 v[56:59], v[162:165], v[210:213], v[56:59]
	v_mfma_f32_16x16x32_bf16 v[60:63], v[128:131], v[206:209], v[60:63]
	v_mfma_f32_16x16x32_bf16 v[60:63], v[132:135], v[210:213], v[60:63]
	s_setprio 0
	s_add_i32 s59, s59, 2
	s_add_u32 s18, s18, 0x100
	s_addc_u32 s19, s19, 0
	s_add_u32 s57, s57, 0x100
	s_addc_u32 s58, s58, 0
	s_cmpk_gt_u32 s59, 0xfd
